# GEMM MMA clusters without the s_setprio 1/0 toggles (all 5 GEMM instantiations); rest identical to v29
# speedup vs baseline: 1.0193x; 1.0193x over previous
; #define PG8_STAGE(bufoff, gbase, voff) do { _Pragma("unroll") for (int _i = 0; _i < 2; ++_i) \
;         __builtin_amdgcn_global_load_lds((const unsigned*)((const char*)(gbase) + (voff)[_i]), (PG8_LAS unsigned*)(lds + (bufoff) + ldsw + _i * 8192), 16, 0, 0); } while (0)
; #define PG8_LDA(dst, b, h) do { _Pragma("unroll") for (int m = 0; m < 4; ++m) _Pragma("unroll") for (int k = 0; k < 2; ++k) dst[m][k] = *(const PG8_LAS bf16x8*)(lds + PG8_SA(b, h) + aoff + m * 2048 + k * 1024); } while (0)
; #define PG8_LDB(dst, b, h) do { _Pragma("unroll") for (int n = 0; n < 2; ++n) _Pragma("unroll") for (int k = 0; k < 2; ++k) dst[n][k] = *(const PG8_LAS bf16x8*)(lds + PG8_SB(b, h) + boff + n * 2048 + k * 1024); } while (0)
; #define PG8_MMA(ai, bj, At, Bt) do { __builtin_amdgcn_s_setprio(1); _Pragma("unroll") for (int m = 0; m < 4; ++m) _Pragma("unroll") for (int n = 0; n < 2; ++n) _Pragma("unroll") for (int k = 0; k < 2; ++k) \
;         acc[ai][bj][m][n] = __builtin_amdgcn_mfma_f32_16x16x32_bf16(Bt[n][k], At[m][k], acc[ai][bj][m][n], 0, 0, 0); __builtin_amdgcn_s_setprio(0); } while (0)
; #define PG8_WAIT_V(n) asm volatile("s_waitcnt vmcnt(" #n ")" ::: "memory")
; #define PG8_WAIT_L(n) asm volatile("s_waitcnt lgkmcnt(" #n ")" ::: "memory")
; #define PG8_BAR __builtin_amdgcn_s_barrier()
; #define PG8_SCHED __builtin_amdgcn_sched_barrier(0)
; template <class Epi, class Sched, bool ALIGN_EPI = false, bool SP2 = false>
; __device__ __forceinline__ void gemm_phase(PG8_LAS unsigned char* lds, const Gemm g, const Sched& S, const Epi& E) {
;     ...
;             PG8_LDB(B0, 0, 0); PG8_LDB(B1, 0, 1); PG8_SCHED; PG8_LDA(At, 0, 0); PG8_STAGE(PG8_SA(1, 1), a1 + hstep, voffA);
;             PG8_WAIT_V(8); PG8_WAIT_L(0); PG8_BAR; PG8_MMA(0, 0, At, B0); PG8_MMA(0, 1, At, B1); PG8_BAR; PG8_SCHED;
;             PG8_LDA(At, 0, 1); PG8_STAGE(PG8_SB(0, 0), b2, voffB); PG8_STAGE(PG8_SB(0, 1), b2 + hstep, voffB); PG8_STAGE(PG8_SA(0, 0), a2, voffA);
;             PG8_WAIT_V(8); PG8_WAIT_L(0); PG8_BAR; PG8_MMA(1, 0, At, B0); PG8_MMA(1, 1, At, B1); PG8_BAR; PG8_SCHED;
.LBB0_180:
	s_add_u32 s6, s4, 0xfffc0080
	s_addc_u32 s7, s5, -1
	s_add_i32 s34, 0, 0x10000
	s_cmp_eq_u32 s49, 12
	s_cselect_b32 s43, s15, s7
	s_cselect_b32 s42, s26, s6
	s_cselect_b32 s7, s27, s47
	s_cselect_b32 s6, s44, s45
	s_add_i32 s35, 0, 0x14000
	v_add_u32_e32 v158, s34, v152
	v_add_u32_e32 v174, s35, v152
	ds_read_b128 v[144:147], v158
	ds_read_b128 v[148:151], v158 offset:1024
	ds_read_b128 v[154:157], v158 offset:2048
	ds_read_b128 v[158:161], v158 offset:3072
	ds_read_b128 v[162:165], v174
	ds_read_b128 v[166:169], v174 offset:1024
	ds_read_b128 v[170:173], v174 offset:2048
	ds_read_b128 v[174:177], v174 offset:3072
	v_lshl_add_u64 v[178:179], s[4:5], 0, v[140:141]
	s_add_i32 m0, s18, 0xc000
	ds_read_b128 v[184:187], v153
	ds_read_b128 v[188:191], v153 offset:1024
	ds_read_b128 v[192:195], v153 offset:2048
	ds_read_b128 v[196:199], v153 offset:3072
	ds_read_b128 v[210:213], v153 offset:4096
	ds_read_b128 v[214:217], v153 offset:5120
	ds_read_b128 v[218:221], v153 offset:6144
	ds_read_b128 v[222:225], v153 offset:7168
	global_load_lds_dwordx4 v[178:179], off
	v_lshl_add_u64 v[178:179], s[4:5], 0, v[142:143]
	s_add_i32 m0, s18, 0xe000
	s_nop 0
	global_load_lds_dwordx4 v[178:179], off
	s_waitcnt vmcnt(8)
	s_waitcnt lgkmcnt(0)
	s_barrier
	s_waitcnt lgkmcnt(0)
	v_mfma_f32_16x16x32_bf16 v[124:127], v[144:147], v[184:187], v[124:127]
	v_mfma_f32_16x16x32_bf16 v[120:123], v[154:157], v[184:187], v[120:123]
	v_mfma_f32_16x16x32_bf16 v[108:111], v[144:147], v[192:195], v[108:111]
	v_mfma_f32_16x16x32_bf16 v[104:107], v[154:157], v[192:195], v[104:107]
	v_mfma_f32_16x16x32_bf16 v[92:95], v[144:147], v[210:213], v[92:95]
	v_mfma_f32_16x16x32_bf16 v[88:91], v[154:157], v[210:213], v[88:91]
	v_mfma_f32_16x16x32_bf16 v[76:79], v[144:147], v[218:221], v[76:79]
	v_mfma_f32_16x16x32_bf16 v[72:75], v[154:157], v[218:221], v[72:75]
	v_mfma_f32_16x16x32_bf16 v[124:127], v[148:151], v[188:191], v[124:127]
	v_mfma_f32_16x16x32_bf16 v[120:123], v[158:161], v[188:191], v[120:123]
	v_mfma_f32_16x16x32_bf16 v[108:111], v[148:151], v[196:199], v[108:111]
	v_mfma_f32_16x16x32_bf16 v[104:107], v[158:161], v[196:199], v[104:107]
	v_mfma_f32_16x16x32_bf16 v[92:95], v[148:151], v[214:217], v[92:95]
	v_mfma_f32_16x16x32_bf16 v[88:91], v[158:161], v[214:217], v[88:91]
	v_mfma_f32_16x16x32_bf16 v[76:79], v[148:151], v[222:225], v[76:79]
	v_mfma_f32_16x16x32_bf16 v[72:75], v[158:161], v[222:225], v[72:75]
	v_mfma_f32_16x16x32_bf16 v[116:119], v[162:165], v[184:187], v[116:119]
	v_mfma_f32_16x16x32_bf16 v[112:115], v[170:173], v[184:187], v[112:115]
	v_mfma_f32_16x16x32_bf16 v[100:103], v[162:165], v[192:195], v[100:103]
	v_mfma_f32_16x16x32_bf16 v[96:99], v[170:173], v[192:195], v[96:99]
	v_mfma_f32_16x16x32_bf16 v[84:87], v[162:165], v[210:213], v[84:87]
	v_mfma_f32_16x16x32_bf16 v[80:83], v[170:173], v[210:213], v[80:83]
	v_mfma_f32_16x16x32_bf16 v[68:71], v[162:165], v[218:221], v[68:71]
	v_mfma_f32_16x16x32_bf16 v[64:67], v[170:173], v[218:221], v[64:67]
	v_mfma_f32_16x16x32_bf16 v[116:119], v[166:169], v[188:191], v[116:119]
	v_mfma_f32_16x16x32_bf16 v[112:115], v[174:177], v[188:191], v[112:115]
	v_mfma_f32_16x16x32_bf16 v[100:103], v[166:169], v[196:199], v[100:103]
	v_mfma_f32_16x16x32_bf16 v[96:99], v[174:177], v[196:199], v[96:99]
	v_mfma_f32_16x16x32_bf16 v[84:87], v[166:169], v[214:217], v[84:87]
	v_mfma_f32_16x16x32_bf16 v[80:83], v[174:177], v[214:217], v[80:83]
	v_mfma_f32_16x16x32_bf16 v[68:71], v[166:169], v[222:225], v[68:71]
	v_mfma_f32_16x16x32_bf16 v[64:67], v[174:177], v[222:225], v[64:67]
	s_barrier
	s_add_i32 s34, s34, s17
	v_lshl_add_u64 v[178:179], s[6:7], 0, v[132:133]
	s_mov_b32 m0, s34
	ds_read_b128 v[184:187], v153 offset:16384
	ds_read_b128 v[188:191], v153 offset:17408
	ds_read_b128 v[192:195], v153 offset:18432
	ds_read_b128 v[196:199], v153 offset:19456
	ds_read_b128 v[210:213], v153 offset:20480
	ds_read_b128 v[214:217], v153 offset:21504
	ds_read_b128 v[218:221], v153 offset:22528
	ds_read_b128 v[222:225], v153 offset:23552
	global_load_lds_dwordx4 v[178:179], off
	s_add_i32 m0, s34, 0x2000
	s_add_u32 s60, s6, 0x40000
	v_lshl_add_u64 v[200:201], s[6:7], 0, v[128:129]
	s_addc_u32 s61, s7, 0
	s_add_i32 s34, s35, s17
	global_load_lds_dwordx4 v[200:201], off
	v_lshl_add_u64 v[226:227], s[60:61], 0, v[132:133]
	s_mov_b32 m0, s34
	v_lshl_add_u64 v[228:229], s[42:43], 0, v[130:131]
	global_load_lds_dwordx4 v[226:227], off
	v_lshl_add_u64 v[226:227], s[60:61], 0, v[128:129]
	s_add_i32 m0, s34, 0x2000
	s_nop 0
	global_load_lds_dwordx4 v[226:227], off
	v_lshl_add_u64 v[226:227], s[42:43], 0, v[134:135]
	s_mov_b32 m0, s18
	s_nop 0
	global_load_lds_dwordx4 v[226:227], off
	s_mov_b32 m0, s19
	s_nop 0
	global_load_lds_dwordx4 v[228:229], off
	s_waitcnt vmcnt(8)
	s_waitcnt lgkmcnt(0)
	s_barrier
; #define PG8_STAGE(bufoff, gbase, voff) do { _Pragma("unroll") for (int _i = 0; _i < 2; ++_i) \
;         __builtin_amdgcn_global_load_lds((const unsigned*)((const char*)(gbase) + (voff)[_i]), (PG8_LAS unsigned*)(lds + (bufoff) + ldsw + _i * 8192), 16, 0, 0); } while (0)
; #define PG8_LDA(dst, b, h) do { _Pragma("unroll") for (int m = 0; m < 4; ++m) _Pragma("unroll") for (int k = 0; k < 2; ++k) dst[m][k] = *(const PG8_LAS bf16x8*)(lds + PG8_SA(b, h) + aoff + m * 2048 + k * 1024); } while (0)
; #define PG8_LDB(dst, b, h) do { _Pragma("unroll") for (int n = 0; n < 2; ++n) _Pragma("unroll") for (int k = 0; k < 2; ++k) dst[n][k] = *(const PG8_LAS bf16x8*)(lds + PG8_SB(b, h) + boff + n * 2048 + k * 1024); } while (0)
; #define PG8_MMA(ai, bj, At, Bt) do { __builtin_amdgcn_s_setprio(1); _Pragma("unroll") for (int m = 0; m < 4; ++m) _Pragma("unroll") for (int n = 0; n < 2; ++n) _Pragma("unroll") for (int k = 0; k < 2; ++k) \
;         acc[ai][bj][m][n] = __builtin_amdgcn_mfma_f32_16x16x32_bf16(Bt[n][k], At[m][k], acc[ai][bj][m][n], 0, 0, 0); __builtin_amdgcn_s_setprio(0); } while (0)
; #define PG8_WAIT_V(n) asm volatile("s_waitcnt vmcnt(" #n ")" ::: "memory")
; #define PG8_WAIT_L(n) asm volatile("s_waitcnt lgkmcnt(" #n ")" ::: "memory")
; #define PG8_BAR __builtin_amdgcn_s_barrier()
; #define PG8_SCHED __builtin_amdgcn_sched_barrier(0)
; template <class Epi, class Sched, bool ALIGN_EPI = false, bool SP2 = false>
; __device__ __forceinline__ void gemm_phase(PG8_LAS unsigned char* lds, const Gemm g, const Sched& S, const Epi& E) {
;     ...
;             PG8_WAIT_V(8); PG8_WAIT_L(0); PG8_BAR; PG8_MMA(1, 0, At, B0); PG8_MMA(1, 1, At, B1); PG8_BAR; PG8_SCHED;
;             PG8_LDB(B0, 1, 0); PG8_LDB(B1, 1, 1); PG8_SCHED; PG8_LDA(At, 1, 0); PG8_STAGE(PG8_SA(0, 1), a2 + hstep, voffA);
;             PG8_WAIT_V(8); PG8_WAIT_L(0); PG8_BAR; PG8_MMA(0, 0, At, B0); PG8_MMA(0, 1, At, B1); PG8_BAR; PG8_SCHED;
;             PG8_LDA(At, 1, 1); PG8_STAGE(PG8_SB(1, 0), b3, voffB); PG8_STAGE(PG8_SB(1, 1), b3 + hstep, voffB); PG8_STAGE(PG8_SA(1, 0), a3, voffA);
	s_waitcnt lgkmcnt(0)
	v_mfma_f32_16x16x32_bf16 v[60:63], v[144:147], v[184:187], v[60:63]
	v_mfma_f32_16x16x32_bf16 v[56:59], v[154:157], v[184:187], v[56:59]
	v_mfma_f32_16x16x32_bf16 v[44:47], v[144:147], v[192:195], v[44:47]
	v_mfma_f32_16x16x32_bf16 v[40:43], v[154:157], v[192:195], v[40:43]
	v_mfma_f32_16x16x32_bf16 v[28:31], v[144:147], v[210:213], v[28:31]
	v_mfma_f32_16x16x32_bf16 v[24:27], v[154:157], v[210:213], v[24:27]
	v_mfma_f32_16x16x32_bf16 v[12:15], v[144:147], v[218:221], v[12:15]
	v_mfma_f32_16x16x32_bf16 v[8:11], v[154:157], v[218:221], v[8:11]
	v_mfma_f32_16x16x32_bf16 v[60:63], v[148:151], v[188:191], v[60:63]
	v_mfma_f32_16x16x32_bf16 v[56:59], v[158:161], v[188:191], v[56:59]
	v_mfma_f32_16x16x32_bf16 v[44:47], v[148:151], v[196:199], v[44:47]
	v_mfma_f32_16x16x32_bf16 v[40:43], v[158:161], v[196:199], v[40:43]
	v_mfma_f32_16x16x32_bf16 v[28:31], v[148:151], v[214:217], v[28:31]
	v_mfma_f32_16x16x32_bf16 v[24:27], v[158:161], v[214:217], v[24:27]
	v_mfma_f32_16x16x32_bf16 v[12:15], v[148:151], v[222:225], v[12:15]
	v_mfma_f32_16x16x32_bf16 v[8:11], v[158:161], v[222:225], v[8:11]
	v_mfma_f32_16x16x32_bf16 v[52:55], v[162:165], v[184:187], v[52:55]
	v_mfma_f32_16x16x32_bf16 v[48:51], v[170:173], v[184:187], v[48:51]
	v_mfma_f32_16x16x32_bf16 v[36:39], v[162:165], v[192:195], v[36:39]
	v_mfma_f32_16x16x32_bf16 v[32:35], v[170:173], v[192:195], v[32:35]
	v_mfma_f32_16x16x32_bf16 v[20:23], v[162:165], v[210:213], v[20:23]
	v_mfma_f32_16x16x32_bf16 v[16:19], v[170:173], v[210:213], v[16:19]
	v_mfma_f32_16x16x32_bf16 v[4:7], v[162:165], v[218:221], v[4:7]
	v_mfma_f32_16x16x32_bf16 v[0:3], v[170:173], v[218:221], v[0:3]
	v_mfma_f32_16x16x32_bf16 v[52:55], v[166:169], v[188:191], v[52:55]
	v_mfma_f32_16x16x32_bf16 v[48:51], v[174:177], v[188:191], v[48:51]
	v_mfma_f32_16x16x32_bf16 v[36:39], v[166:169], v[196:199], v[36:39]
	v_mfma_f32_16x16x32_bf16 v[32:35], v[174:177], v[196:199], v[32:35]
	v_mfma_f32_16x16x32_bf16 v[20:23], v[166:169], v[214:217], v[20:23]
	v_mfma_f32_16x16x32_bf16 v[16:19], v[174:177], v[214:217], v[16:19]
	v_mfma_f32_16x16x32_bf16 v[4:7], v[166:169], v[222:225], v[4:7]
	v_mfma_f32_16x16x32_bf16 v[0:3], v[174:177], v[222:225], v[0:3]
	s_barrier
	s_add_i32 s34, 0, 0x18000
	s_add_i32 s35, 0, 0x1c000
	v_add_u32_e32 v158, s34, v152
	v_add_u32_e32 v174, s35, v152
	ds_read_b128 v[144:147], v158
	ds_read_b128 v[148:151], v158 offset:1024
	ds_read_b128 v[154:157], v158 offset:2048
	ds_read_b128 v[158:161], v158 offset:3072
	ds_read_b128 v[162:165], v174
	ds_read_b128 v[166:169], v174 offset:1024
	ds_read_b128 v[170:173], v174 offset:2048
	ds_read_b128 v[174:177], v174 offset:3072
	s_add_u32 s42, s42, 0x40000
	s_addc_u32 s43, s43, 0
	s_mov_b32 m0, s20
	v_lshl_add_u64 v[230:231], s[42:43], 0, v[134:135]
	ds_read_b128 v[184:187], v153 offset:32768
	ds_read_b128 v[188:191], v153 offset:33792
	ds_read_b128 v[192:195], v153 offset:34816
	ds_read_b128 v[196:199], v153 offset:35840
	ds_read_b128 v[210:213], v153 offset:36864
	ds_read_b128 v[214:217], v153 offset:37888
	ds_read_b128 v[218:221], v153 offset:38912
	ds_read_b128 v[222:225], v153 offset:39936
	global_load_lds_dwordx4 v[230:231], off
	v_lshl_add_u64 v[230:231], s[42:43], 0, v[130:131]
	s_mov_b32 m0, s21
	s_nop 0
	global_load_lds_dwordx4 v[230:231], off
	s_waitcnt vmcnt(8)
	s_waitcnt lgkmcnt(0)
	s_barrier
	s_waitcnt lgkmcnt(0)
	v_mfma_f32_16x16x32_bf16 v[124:127], v[144:147], v[184:187], v[124:127]
	v_mfma_f32_16x16x32_bf16 v[120:123], v[154:157], v[184:187], v[120:123]
	v_mfma_f32_16x16x32_bf16 v[108:111], v[144:147], v[192:195], v[108:111]
	v_mfma_f32_16x16x32_bf16 v[104:107], v[154:157], v[192:195], v[104:107]
	v_mfma_f32_16x16x32_bf16 v[92:95], v[144:147], v[210:213], v[92:95]
	v_mfma_f32_16x16x32_bf16 v[88:91], v[154:157], v[210:213], v[88:91]
	v_mfma_f32_16x16x32_bf16 v[76:79], v[144:147], v[218:221], v[76:79]
	v_mfma_f32_16x16x32_bf16 v[72:75], v[154:157], v[218:221], v[72:75]
	v_mfma_f32_16x16x32_bf16 v[124:127], v[148:151], v[188:191], v[124:127]
	v_mfma_f32_16x16x32_bf16 v[120:123], v[158:161], v[188:191], v[120:123]
	v_mfma_f32_16x16x32_bf16 v[108:111], v[148:151], v[196:199], v[108:111]
	v_mfma_f32_16x16x32_bf16 v[104:107], v[158:161], v[196:199], v[104:107]
	v_mfma_f32_16x16x32_bf16 v[92:95], v[148:151], v[214:217], v[92:95]
	v_mfma_f32_16x16x32_bf16 v[88:91], v[158:161], v[214:217], v[88:91]
	v_mfma_f32_16x16x32_bf16 v[76:79], v[148:151], v[222:225], v[76:79]
	v_mfma_f32_16x16x32_bf16 v[72:75], v[158:161], v[222:225], v[72:75]
	v_mfma_f32_16x16x32_bf16 v[116:119], v[162:165], v[184:187], v[116:119]
	v_mfma_f32_16x16x32_bf16 v[112:115], v[170:173], v[184:187], v[112:115]
	v_mfma_f32_16x16x32_bf16 v[100:103], v[162:165], v[192:195], v[100:103]
	v_mfma_f32_16x16x32_bf16 v[96:99], v[170:173], v[192:195], v[96:99]
	v_mfma_f32_16x16x32_bf16 v[84:87], v[162:165], v[210:213], v[84:87]
	v_mfma_f32_16x16x32_bf16 v[80:83], v[170:173], v[210:213], v[80:83]
	v_mfma_f32_16x16x32_bf16 v[68:71], v[162:165], v[218:221], v[68:71]
	v_mfma_f32_16x16x32_bf16 v[64:67], v[170:173], v[218:221], v[64:67]
	v_mfma_f32_16x16x32_bf16 v[116:119], v[166:169], v[188:191], v[116:119]
	v_mfma_f32_16x16x32_bf16 v[112:115], v[174:177], v[188:191], v[112:115]
	v_mfma_f32_16x16x32_bf16 v[100:103], v[166:169], v[196:199], v[100:103]
	v_mfma_f32_16x16x32_bf16 v[96:99], v[174:177], v[196:199], v[96:99]
	v_mfma_f32_16x16x32_bf16 v[84:87], v[166:169], v[214:217], v[84:87]
	v_mfma_f32_16x16x32_bf16 v[80:83], v[174:177], v[214:217], v[80:83]
	v_mfma_f32_16x16x32_bf16 v[68:71], v[166:169], v[222:225], v[68:71]
	v_mfma_f32_16x16x32_bf16 v[64:67], v[174:177], v[222:225], v[64:67]
	s_barrier
; #define PG8_STAGE(bufoff, gbase, voff) do { _Pragma("unroll") for (int _i = 0; _i < 2; ++_i) \
;         __builtin_amdgcn_global_load_lds((const unsigned*)((const char*)(gbase) + (voff)[_i]), (PG8_LAS unsigned*)(lds + (bufoff) + ldsw + _i * 8192), 16, 0, 0); } while (0)
; #define PG8_LDA(dst, b, h) do { _Pragma("unroll") for (int m = 0; m < 4; ++m) _Pragma("unroll") for (int k = 0; k < 2; ++k) dst[m][k] = *(const PG8_LAS bf16x8*)(lds + PG8_SA(b, h) + aoff + m * 2048 + k * 1024); } while (0)
; #define PG8_MMA(ai, bj, At, Bt) do { __builtin_amdgcn_s_setprio(1); _Pragma("unroll") for (int m = 0; m < 4; ++m) _Pragma("unroll") for (int n = 0; n < 2; ++n) _Pragma("unroll") for (int k = 0; k < 2; ++k) \
;         acc[ai][bj][m][n] = __builtin_amdgcn_mfma_f32_16x16x32_bf16(Bt[n][k], At[m][k], acc[ai][bj][m][n], 0, 0, 0); __builtin_amdgcn_s_setprio(0); } while (0)
; #define PG8_WAIT_V(n) asm volatile("s_waitcnt vmcnt(" #n ")" ::: "memory")
; #define PG8_WAIT_L(n) asm volatile("s_waitcnt lgkmcnt(" #n ")" ::: "memory")
; #define PG8_BAR __builtin_amdgcn_s_barrier()
; #define PG8_SCHED __builtin_amdgcn_sched_barrier(0)
; template <class Epi, class Sched, bool ALIGN_EPI = false, bool SP2 = false>
; __device__ __forceinline__ void gemm_phase(PG8_LAS unsigned char* lds, const Gemm g, const Sched& S, const Epi& E) {
;     ...
;             PG8_LDA(At, 1, 1); PG8_STAGE(PG8_SB(1, 0), b3, voffB); PG8_STAGE(PG8_SB(1, 1), b3 + hstep, voffB); PG8_STAGE(PG8_SA(1, 0), a3, voffA);
;             PG8_WAIT_V(8); PG8_WAIT_L(0); PG8_BAR; PG8_MMA(1, 0, At, B0); PG8_MMA(1, 1, At, B1); PG8_BAR; PG8_SCHED;
	s_add_i32 s34, s34, s17
	v_lshl_add_u64 v[178:179], v[178:179], 0, s[58:59]
	s_mov_b32 m0, s34
	ds_read_b128 v[184:187], v153 offset:49152
	ds_read_b128 v[188:191], v153 offset:50176
	ds_read_b128 v[192:195], v153 offset:51200
	ds_read_b128 v[196:199], v153 offset:52224
	ds_read_b128 v[210:213], v153 offset:53248
	ds_read_b128 v[214:217], v153 offset:54272
	ds_read_b128 v[218:221], v153 offset:55296
	ds_read_b128 v[222:225], v153 offset:56320
	global_load_lds_dwordx4 v[178:179], off
	s_add_i32 m0, s34, 0x2000
	s_add_u32 s6, s6, 0x40080
	v_lshl_add_u64 v[178:179], v[200:201], 0, s[58:59]
	s_addc_u32 s7, s7, 0
	s_add_i32 s34, s35, s17
	global_load_lds_dwordx4 v[178:179], off
	v_lshl_add_u64 v[178:179], s[6:7], 0, v[132:133]
	s_mov_b32 m0, s34
	s_nop 0
	global_load_lds_dwordx4 v[178:179], off
	v_lshl_add_u64 v[178:179], s[6:7], 0, v[128:129]
	s_add_i32 m0, s34, 0x2000
	s_nop 0
	global_load_lds_dwordx4 v[178:179], off
	v_lshl_add_u64 v[178:179], v[226:227], 0, s[58:59]
	s_mov_b32 m0, s24
	s_nop 0
	global_load_lds_dwordx4 v[178:179], off
	v_lshl_add_u64 v[178:179], v[228:229], 0, s[58:59]
	s_mov_b32 m0, s25
	s_nop 0
	global_load_lds_dwordx4 v[178:179], off
	s_waitcnt vmcnt(8)
	s_waitcnt lgkmcnt(0)
	s_barrier
	s_waitcnt lgkmcnt(0)
	v_mfma_f32_16x16x32_bf16 v[60:63], v[144:147], v[184:187], v[60:63]
	v_mfma_f32_16x16x32_bf16 v[56:59], v[154:157], v[184:187], v[56:59]
	v_mfma_f32_16x16x32_bf16 v[44:47], v[144:147], v[192:195], v[44:47]
	v_mfma_f32_16x16x32_bf16 v[40:43], v[154:157], v[192:195], v[40:43]
	v_mfma_f32_16x16x32_bf16 v[28:31], v[144:147], v[210:213], v[28:31]
	v_mfma_f32_16x16x32_bf16 v[24:27], v[154:157], v[210:213], v[24:27]
	v_mfma_f32_16x16x32_bf16 v[12:15], v[144:147], v[218:221], v[12:15]
	v_mfma_f32_16x16x32_bf16 v[8:11], v[154:157], v[218:221], v[8:11]
	v_mfma_f32_16x16x32_bf16 v[60:63], v[148:151], v[188:191], v[60:63]
	v_mfma_f32_16x16x32_bf16 v[56:59], v[158:161], v[188:191], v[56:59]
	v_mfma_f32_16x16x32_bf16 v[44:47], v[148:151], v[196:199], v[44:47]
	v_mfma_f32_16x16x32_bf16 v[40:43], v[158:161], v[196:199], v[40:43]
	v_mfma_f32_16x16x32_bf16 v[28:31], v[148:151], v[214:217], v[28:31]
	v_mfma_f32_16x16x32_bf16 v[24:27], v[158:161], v[214:217], v[24:27]
	v_mfma_f32_16x16x32_bf16 v[12:15], v[148:151], v[222:225], v[12:15]
	v_mfma_f32_16x16x32_bf16 v[8:11], v[158:161], v[222:225], v[8:11]
	v_mfma_f32_16x16x32_bf16 v[52:55], v[162:165], v[184:187], v[52:55]
	v_mfma_f32_16x16x32_bf16 v[48:51], v[170:173], v[184:187], v[48:51]
	v_mfma_f32_16x16x32_bf16 v[36:39], v[162:165], v[192:195], v[36:39]
	v_mfma_f32_16x16x32_bf16 v[32:35], v[170:173], v[192:195], v[32:35]
	v_mfma_f32_16x16x32_bf16 v[20:23], v[162:165], v[210:213], v[20:23]
	v_mfma_f32_16x16x32_bf16 v[16:19], v[170:173], v[210:213], v[16:19]
	v_mfma_f32_16x16x32_bf16 v[4:7], v[162:165], v[218:221], v[4:7]
	v_mfma_f32_16x16x32_bf16 v[0:3], v[170:173], v[218:221], v[0:3]
	v_mfma_f32_16x16x32_bf16 v[52:55], v[166:169], v[188:191], v[52:55]
	v_mfma_f32_16x16x32_bf16 v[48:51], v[174:177], v[188:191], v[48:51]
	v_mfma_f32_16x16x32_bf16 v[36:39], v[166:169], v[196:199], v[36:39]
	v_mfma_f32_16x16x32_bf16 v[32:35], v[174:177], v[196:199], v[32:35]
	v_mfma_f32_16x16x32_bf16 v[20:23], v[166:169], v[214:217], v[20:23]
	v_mfma_f32_16x16x32_bf16 v[16:19], v[174:177], v[214:217], v[16:19]
	v_mfma_f32_16x16x32_bf16 v[4:7], v[166:169], v[222:225], v[4:7]
	v_mfma_f32_16x16x32_bf16 v[0:3], v[174:177], v[222:225], v[0:3]
	s_barrier
	s_add_i32 s49, s49, 2
	s_add_u32 s4, s4, 0x100
	s_addc_u32 s5, s5, 0
	s_add_u32 s45, s45, 0x100
	s_addc_u32 s47, s47, 0
	s_cmp_gt_u32 s49, 13
	s_cbranch_scc0 .LBB0_180
	s_and_b64 vcc, exec, s[28:29]
	s_cbranch_vccz .LBB0_183
	s_barrier

; #define PG8_STAGE(bufoff, gbase, voff) do { _Pragma("unroll") for (int _i = 0; _i < 2; ++_i) \
;         __builtin_amdgcn_global_load_lds((const unsigned*)((const char*)(gbase) + (voff)[_i]), (PG8_LAS unsigned*)(lds + (bufoff) + ldsw + _i * 8192), 16, 0, 0); } while (0)
; #define PG8_LDA(dst, b, h) do { _Pragma("unroll") for (int m = 0; m < 4; ++m) _Pragma("unroll") for (int k = 0; k < 2; ++k) dst[m][k] = *(const PG8_LAS bf16x8*)(lds + PG8_SA(b, h) + aoff + m * 2048 + k * 1024); } while (0)
; #define PG8_LDB(dst, b, h) do { _Pragma("unroll") for (int n = 0; n < 2; ++n) _Pragma("unroll") for (int k = 0; k < 2; ++k) dst[n][k] = *(const PG8_LAS bf16x8*)(lds + PG8_SB(b, h) + boff + n * 2048 + k * 1024); } while (0)
; #define PG8_MMA(ai, bj, At, Bt) do { __builtin_amdgcn_s_setprio(1); _Pragma("unroll") for (int m = 0; m < 4; ++m) _Pragma("unroll") for (int n = 0; n < 2; ++n) _Pragma("unroll") for (int k = 0; k < 2; ++k) \
;         acc[ai][bj][m][n] = __builtin_amdgcn_mfma_f32_16x16x32_bf16(Bt[n][k], At[m][k], acc[ai][bj][m][n], 0, 0, 0); __builtin_amdgcn_s_setprio(0); } while (0)
; #define PG8_WAIT_V(n) asm volatile("s_waitcnt vmcnt(" #n ")" ::: "memory")
; #define PG8_WAIT_L(n) asm volatile("s_waitcnt lgkmcnt(" #n ")" ::: "memory")
; #define PG8_BAR __builtin_amdgcn_s_barrier()
; #define PG8_SCHED __builtin_amdgcn_sched_barrier(0)
; template <class Epi, class Sched, bool ALIGN_EPI = false, bool SP2 = false>
; __device__ __forceinline__ void gemm_phase(PG8_LAS unsigned char* lds, const Gemm g, const Sched& S, const Epi& E) {
;     ...
;             PG8_LDB(B0, 0, 0); PG8_LDB(B1, 0, 1); PG8_SCHED; PG8_LDA(At, 0, 0); PG8_STAGE(PG8_SA(1, 1), a1 + hstep, voffA);
;             PG8_WAIT_V(8); PG8_WAIT_L(0); PG8_BAR; PG8_MMA(0, 0, At, B0); PG8_MMA(0, 1, At, B1); PG8_BAR; PG8_SCHED;
;             PG8_LDA(At, 0, 1); PG8_STAGE(PG8_SB(0, 0), b2, voffB); PG8_STAGE(PG8_SB(0, 1), b2 + hstep, voffB); PG8_STAGE(PG8_SA(0, 0), a2, voffA);
;             PG8_WAIT_V(8); PG8_WAIT_L(0); PG8_BAR; PG8_MMA(1, 0, At, B0); PG8_MMA(1, 1, At, B1); PG8_BAR; PG8_SCHED;
.LBB0_481:
	s_add_i32 s61, s46, 2
	s_add_u32 s34, s6, 0x80
	s_addc_u32 s35, s7, 0
	s_add_i32 s64, 0, 0x10000
	s_cmp_eq_u32 s25, s46
	s_cselect_b32 s47, s1, s35
	s_cselect_b32 s46, s0, s34
	v_add_u32_e32 v143, s64, v141
	s_cselect_b32 s63, s45, s60
	s_cselect_b32 s62, s44, s53
	s_add_i32 s34, 0, 0x14000
	ds_read_b128 v[144:147], v143
	ds_read_b128 v[148:151], v143 offset:1024
	ds_read_b128 v[152:155], v143 offset:2048
	ds_read_b128 v[156:159], v143 offset:3072
	v_add_u32_e32 v143, s34, v141
	ds_read_b128 v[160:163], v143
	ds_read_b128 v[164:167], v143 offset:1024
	ds_read_b128 v[168:171], v143 offset:2048
	ds_read_b128 v[172:175], v143 offset:3072
	v_lshl_add_u64 v[200:201], s[6:7], 0, v[136:137]
	s_add_i32 m0, s18, 0xc000
	ds_read_b128 v[176:179], v142
	ds_read_b128 v[184:187], v142 offset:1024
	ds_read_b128 v[188:191], v142 offset:2048
	ds_read_b128 v[192:195], v142 offset:3072
	ds_read_b128 v[196:199], v142 offset:4096
	ds_read_b128 v[210:213], v142 offset:5120
	ds_read_b128 v[214:217], v142 offset:6144
	ds_read_b128 v[218:221], v142 offset:7168
	global_load_lds_dwordx4 v[200:201], off
	v_lshl_add_u64 v[200:201], s[6:7], 0, v[138:139]
	s_add_i32 m0, s18, 0xe000
	s_nop 0
	global_load_lds_dwordx4 v[200:201], off
	s_waitcnt vmcnt(8)
	s_waitcnt lgkmcnt(0)
	s_barrier
	s_waitcnt lgkmcnt(0)
	v_mfma_f32_16x16x32_bf16 v[120:123], v[144:147], v[176:179], v[120:123]
	v_mfma_f32_16x16x32_bf16 v[124:127], v[152:155], v[176:179], v[124:127]
	v_mfma_f32_16x16x32_bf16 v[108:111], v[144:147], v[188:191], v[108:111]
	v_mfma_f32_16x16x32_bf16 v[104:107], v[152:155], v[188:191], v[104:107]
	v_mfma_f32_16x16x32_bf16 v[92:95], v[144:147], v[196:199], v[92:95]
	v_mfma_f32_16x16x32_bf16 v[88:91], v[152:155], v[196:199], v[88:91]
	v_mfma_f32_16x16x32_bf16 v[76:79], v[144:147], v[214:217], v[76:79]
	v_mfma_f32_16x16x32_bf16 v[72:75], v[152:155], v[214:217], v[72:75]
	v_mfma_f32_16x16x32_bf16 v[120:123], v[148:151], v[184:187], v[120:123]
	v_mfma_f32_16x16x32_bf16 v[124:127], v[156:159], v[184:187], v[124:127]
	v_mfma_f32_16x16x32_bf16 v[108:111], v[148:151], v[192:195], v[108:111]
	v_mfma_f32_16x16x32_bf16 v[104:107], v[156:159], v[192:195], v[104:107]
	v_mfma_f32_16x16x32_bf16 v[92:95], v[148:151], v[210:213], v[92:95]
	v_mfma_f32_16x16x32_bf16 v[88:91], v[156:159], v[210:213], v[88:91]
	v_mfma_f32_16x16x32_bf16 v[76:79], v[148:151], v[218:221], v[76:79]
	v_mfma_f32_16x16x32_bf16 v[72:75], v[156:159], v[218:221], v[72:75]
	v_mfma_f32_16x16x32_bf16 v[116:119], v[160:163], v[176:179], v[116:119]
	v_mfma_f32_16x16x32_bf16 v[112:115], v[168:171], v[176:179], v[112:115]
	v_mfma_f32_16x16x32_bf16 v[100:103], v[160:163], v[188:191], v[100:103]
	v_mfma_f32_16x16x32_bf16 v[96:99], v[168:171], v[188:191], v[96:99]
	v_mfma_f32_16x16x32_bf16 v[84:87], v[160:163], v[196:199], v[84:87]
	v_mfma_f32_16x16x32_bf16 v[80:83], v[168:171], v[196:199], v[80:83]
	v_mfma_f32_16x16x32_bf16 v[68:71], v[160:163], v[214:217], v[68:71]
	v_mfma_f32_16x16x32_bf16 v[64:67], v[168:171], v[214:217], v[64:67]
	v_mfma_f32_16x16x32_bf16 v[116:119], v[164:167], v[184:187], v[116:119]
	v_mfma_f32_16x16x32_bf16 v[112:115], v[172:175], v[184:187], v[112:115]
	v_mfma_f32_16x16x32_bf16 v[100:103], v[164:167], v[192:195], v[100:103]
	v_mfma_f32_16x16x32_bf16 v[96:99], v[172:175], v[192:195], v[96:99]
	v_mfma_f32_16x16x32_bf16 v[84:87], v[164:167], v[210:213], v[84:87]
	v_mfma_f32_16x16x32_bf16 v[80:83], v[172:175], v[210:213], v[80:83]
	v_mfma_f32_16x16x32_bf16 v[68:71], v[164:167], v[218:221], v[68:71]
	v_mfma_f32_16x16x32_bf16 v[64:67], v[172:175], v[218:221], v[64:67]
	s_barrier
	s_add_i32 s35, s64, s17
	v_lshl_add_u64 v[200:201], s[62:63], 0, v[132:133]
	s_mov_b32 m0, s35
	ds_read_b128 v[176:179], v142 offset:16384
	ds_read_b128 v[184:187], v142 offset:17408
	ds_read_b128 v[188:191], v142 offset:18432
	ds_read_b128 v[192:195], v142 offset:19456
	ds_read_b128 v[196:199], v142 offset:20480
	ds_read_b128 v[210:213], v142 offset:21504
	ds_read_b128 v[214:217], v142 offset:22528
	ds_read_b128 v[218:221], v142 offset:23552
	global_load_lds_dwordx4 v[200:201], off
	s_add_i32 m0, s35, 0x2000
	v_lshl_add_u64 v[222:223], s[62:63], 0, v[128:129]
	s_add_u32 s62, s62, s4
	s_addc_u32 s63, s63, s5
	s_add_i32 s34, s34, s17
	global_load_lds_dwordx4 v[222:223], off
	v_lshl_add_u64 v[224:225], s[62:63], 0, v[132:133]
	s_mov_b32 m0, s34
	v_lshl_add_u64 v[226:227], s[62:63], 0, v[128:129]
	global_load_lds_dwordx4 v[224:225], off
	s_add_i32 m0, s34, 0x2000
	v_lshl_add_u64 v[228:229], s[46:47], 0, v[134:135]
	global_load_lds_dwordx4 v[226:227], off
	s_mov_b32 m0, s18
	v_lshl_add_u64 v[230:231], s[46:47], 0, v[130:131]
	global_load_lds_dwordx4 v[228:229], off
	s_mov_b32 m0, s19
	s_nop 0
	global_load_lds_dwordx4 v[230:231], off
	s_waitcnt vmcnt(8)
	s_waitcnt lgkmcnt(0)
	s_barrier
; #define PG8_STAGE(bufoff, gbase, voff) do { _Pragma("unroll") for (int _i = 0; _i < 2; ++_i) \
;         __builtin_amdgcn_global_load_lds((const unsigned*)((const char*)(gbase) + (voff)[_i]), (PG8_LAS unsigned*)(lds + (bufoff) + ldsw + _i * 8192), 16, 0, 0); } while (0)
; #define PG8_LDA(dst, b, h) do { _Pragma("unroll") for (int m = 0; m < 4; ++m) _Pragma("unroll") for (int k = 0; k < 2; ++k) dst[m][k] = *(const PG8_LAS bf16x8*)(lds + PG8_SA(b, h) + aoff + m * 2048 + k * 1024); } while (0)
; #define PG8_LDB(dst, b, h) do { _Pragma("unroll") for (int n = 0; n < 2; ++n) _Pragma("unroll") for (int k = 0; k < 2; ++k) dst[n][k] = *(const PG8_LAS bf16x8*)(lds + PG8_SB(b, h) + boff + n * 2048 + k * 1024); } while (0)
; #define PG8_MMA(ai, bj, At, Bt) do { __builtin_amdgcn_s_setprio(1); _Pragma("unroll") for (int m = 0; m < 4; ++m) _Pragma("unroll") for (int n = 0; n < 2; ++n) _Pragma("unroll") for (int k = 0; k < 2; ++k) \
;         acc[ai][bj][m][n] = __builtin_amdgcn_mfma_f32_16x16x32_bf16(Bt[n][k], At[m][k], acc[ai][bj][m][n], 0, 0, 0); __builtin_amdgcn_s_setprio(0); } while (0)
; #define PG8_WAIT_V(n) asm volatile("s_waitcnt vmcnt(" #n ")" ::: "memory")
; #define PG8_WAIT_L(n) asm volatile("s_waitcnt lgkmcnt(" #n ")" ::: "memory")
; #define PG8_BAR __builtin_amdgcn_s_barrier()
; #define PG8_SCHED __builtin_amdgcn_sched_barrier(0)
; template <class Epi, class Sched, bool ALIGN_EPI = false, bool SP2 = false>
; __device__ __forceinline__ void gemm_phase(PG8_LAS unsigned char* lds, const Gemm g, const Sched& S, const Epi& E) {
;     ...
;             PG8_WAIT_V(8); PG8_WAIT_L(0); PG8_BAR; PG8_MMA(1, 0, At, B0); PG8_MMA(1, 1, At, B1); PG8_BAR; PG8_SCHED;
;             PG8_LDB(B0, 1, 0); PG8_LDB(B1, 1, 1); PG8_SCHED; PG8_LDA(At, 1, 0); PG8_STAGE(PG8_SA(0, 1), a2 + hstep, voffA);
;             PG8_WAIT_V(8); PG8_WAIT_L(0); PG8_BAR; PG8_MMA(0, 0, At, B0); PG8_MMA(0, 1, At, B1); PG8_BAR; PG8_SCHED;
;             PG8_LDA(At, 1, 1); PG8_STAGE(PG8_SB(1, 0), b3, voffB); PG8_STAGE(PG8_SB(1, 1), b3 + hstep, voffB); PG8_STAGE(PG8_SA(1, 0), a3, voffA);
	s_waitcnt lgkmcnt(0)
	v_mfma_f32_16x16x32_bf16 v[60:63], v[144:147], v[176:179], v[60:63]
	v_mfma_f32_16x16x32_bf16 v[56:59], v[152:155], v[176:179], v[56:59]
	v_mfma_f32_16x16x32_bf16 v[44:47], v[144:147], v[188:191], v[44:47]
	v_mfma_f32_16x16x32_bf16 v[40:43], v[152:155], v[188:191], v[40:43]
	v_mfma_f32_16x16x32_bf16 v[28:31], v[144:147], v[196:199], v[28:31]
	v_mfma_f32_16x16x32_bf16 v[24:27], v[152:155], v[196:199], v[24:27]
	v_mfma_f32_16x16x32_bf16 v[12:15], v[144:147], v[214:217], v[12:15]
	v_mfma_f32_16x16x32_bf16 v[8:11], v[152:155], v[214:217], v[8:11]
	v_mfma_f32_16x16x32_bf16 v[60:63], v[148:151], v[184:187], v[60:63]
	v_mfma_f32_16x16x32_bf16 v[56:59], v[156:159], v[184:187], v[56:59]
	v_mfma_f32_16x16x32_bf16 v[44:47], v[148:151], v[192:195], v[44:47]
	v_mfma_f32_16x16x32_bf16 v[40:43], v[156:159], v[192:195], v[40:43]
	v_mfma_f32_16x16x32_bf16 v[28:31], v[148:151], v[210:213], v[28:31]
	v_mfma_f32_16x16x32_bf16 v[24:27], v[156:159], v[210:213], v[24:27]
	v_mfma_f32_16x16x32_bf16 v[12:15], v[148:151], v[218:221], v[12:15]
	v_mfma_f32_16x16x32_bf16 v[8:11], v[156:159], v[218:221], v[8:11]
	v_mfma_f32_16x16x32_bf16 v[52:55], v[160:163], v[176:179], v[52:55]
	v_mfma_f32_16x16x32_bf16 v[48:51], v[168:171], v[176:179], v[48:51]
	v_mfma_f32_16x16x32_bf16 v[36:39], v[160:163], v[188:191], v[36:39]
	v_mfma_f32_16x16x32_bf16 v[32:35], v[168:171], v[188:191], v[32:35]
	v_mfma_f32_16x16x32_bf16 v[20:23], v[160:163], v[196:199], v[20:23]
	v_mfma_f32_16x16x32_bf16 v[16:19], v[168:171], v[196:199], v[16:19]
	v_mfma_f32_16x16x32_bf16 v[4:7], v[160:163], v[214:217], v[4:7]
	v_mfma_f32_16x16x32_bf16 v[0:3], v[168:171], v[214:217], v[0:3]
	v_mfma_f32_16x16x32_bf16 v[52:55], v[164:167], v[184:187], v[52:55]
	v_mfma_f32_16x16x32_bf16 v[48:51], v[172:175], v[184:187], v[48:51]
	v_mfma_f32_16x16x32_bf16 v[36:39], v[164:167], v[192:195], v[36:39]
	v_mfma_f32_16x16x32_bf16 v[32:35], v[172:175], v[192:195], v[32:35]
	v_mfma_f32_16x16x32_bf16 v[20:23], v[164:167], v[210:213], v[20:23]
	v_mfma_f32_16x16x32_bf16 v[16:19], v[172:175], v[210:213], v[16:19]
	v_mfma_f32_16x16x32_bf16 v[4:7], v[164:167], v[218:221], v[4:7]
	v_mfma_f32_16x16x32_bf16 v[0:3], v[172:175], v[218:221], v[0:3]
	s_barrier
	s_add_i32 s34, 0, 0x18000
	v_add_u32_e32 v143, s34, v141
	s_add_i32 s35, 0, 0x1c000
	ds_read_b128 v[144:147], v143
	ds_read_b128 v[148:151], v143 offset:1024
	ds_read_b128 v[152:155], v143 offset:2048
	ds_read_b128 v[156:159], v143 offset:3072
	v_add_u32_e32 v143, s35, v141
	ds_read_b128 v[160:163], v143
	ds_read_b128 v[164:167], v143 offset:1024
	ds_read_b128 v[168:171], v143 offset:2048
	ds_read_b128 v[172:175], v143 offset:3072
	s_add_u32 s46, s46, s4
	s_addc_u32 s47, s47, s5
	s_mov_b32 m0, s20
	v_lshl_add_u64 v[232:233], s[46:47], 0, v[134:135]
	ds_read_b128 v[176:179], v142 offset:32768
	ds_read_b128 v[184:187], v142 offset:33792
	ds_read_b128 v[188:191], v142 offset:34816
	ds_read_b128 v[192:195], v142 offset:35840
	ds_read_b128 v[196:199], v142 offset:36864
	ds_read_b128 v[210:213], v142 offset:37888
	ds_read_b128 v[214:217], v142 offset:38912
	ds_read_b128 v[218:221], v142 offset:39936
	global_load_lds_dwordx4 v[232:233], off
	v_lshl_add_u64 v[232:233], s[46:47], 0, v[130:131]
	s_mov_b32 m0, s21
	s_nop 0
	global_load_lds_dwordx4 v[232:233], off
	s_waitcnt vmcnt(8)
	s_waitcnt lgkmcnt(0)
	s_barrier
	s_waitcnt lgkmcnt(0)
	v_mfma_f32_16x16x32_bf16 v[120:123], v[144:147], v[176:179], v[120:123]
	v_mfma_f32_16x16x32_bf16 v[124:127], v[152:155], v[176:179], v[124:127]
	v_mfma_f32_16x16x32_bf16 v[108:111], v[144:147], v[188:191], v[108:111]
	v_mfma_f32_16x16x32_bf16 v[104:107], v[152:155], v[188:191], v[104:107]
	v_mfma_f32_16x16x32_bf16 v[92:95], v[144:147], v[196:199], v[92:95]
	v_mfma_f32_16x16x32_bf16 v[88:91], v[152:155], v[196:199], v[88:91]
	v_mfma_f32_16x16x32_bf16 v[76:79], v[144:147], v[214:217], v[76:79]
	v_mfma_f32_16x16x32_bf16 v[72:75], v[152:155], v[214:217], v[72:75]
	v_mfma_f32_16x16x32_bf16 v[120:123], v[148:151], v[184:187], v[120:123]
	v_mfma_f32_16x16x32_bf16 v[124:127], v[156:159], v[184:187], v[124:127]
	v_mfma_f32_16x16x32_bf16 v[108:111], v[148:151], v[192:195], v[108:111]
	v_mfma_f32_16x16x32_bf16 v[104:107], v[156:159], v[192:195], v[104:107]
	v_mfma_f32_16x16x32_bf16 v[92:95], v[148:151], v[210:213], v[92:95]
	v_mfma_f32_16x16x32_bf16 v[88:91], v[156:159], v[210:213], v[88:91]
	v_mfma_f32_16x16x32_bf16 v[76:79], v[148:151], v[218:221], v[76:79]
	v_mfma_f32_16x16x32_bf16 v[72:75], v[156:159], v[218:221], v[72:75]
	v_mfma_f32_16x16x32_bf16 v[116:119], v[160:163], v[176:179], v[116:119]
	v_mfma_f32_16x16x32_bf16 v[112:115], v[168:171], v[176:179], v[112:115]
	v_mfma_f32_16x16x32_bf16 v[100:103], v[160:163], v[188:191], v[100:103]
	v_mfma_f32_16x16x32_bf16 v[96:99], v[168:171], v[188:191], v[96:99]
	v_mfma_f32_16x16x32_bf16 v[84:87], v[160:163], v[196:199], v[84:87]
	v_mfma_f32_16x16x32_bf16 v[80:83], v[168:171], v[196:199], v[80:83]
	v_mfma_f32_16x16x32_bf16 v[68:71], v[160:163], v[214:217], v[68:71]
	v_mfma_f32_16x16x32_bf16 v[64:67], v[168:171], v[214:217], v[64:67]
	v_mfma_f32_16x16x32_bf16 v[116:119], v[164:167], v[184:187], v[116:119]
	v_mfma_f32_16x16x32_bf16 v[112:115], v[172:175], v[184:187], v[112:115]
	v_mfma_f32_16x16x32_bf16 v[100:103], v[164:167], v[192:195], v[100:103]
	v_mfma_f32_16x16x32_bf16 v[96:99], v[172:175], v[192:195], v[96:99]
	v_mfma_f32_16x16x32_bf16 v[84:87], v[164:167], v[210:213], v[84:87]
	v_mfma_f32_16x16x32_bf16 v[80:83], v[172:175], v[210:213], v[80:83]
	v_mfma_f32_16x16x32_bf16 v[68:71], v[164:167], v[218:221], v[68:71]
	v_mfma_f32_16x16x32_bf16 v[64:67], v[172:175], v[218:221], v[64:67]
	s_barrier
; #define PG8_STAGE(bufoff, gbase, voff) do { _Pragma("unroll") for (int _i = 0; _i < 2; ++_i) \
;         __builtin_amdgcn_global_load_lds((const unsigned*)((const char*)(gbase) + (voff)[_i]), (PG8_LAS unsigned*)(lds + (bufoff) + ldsw + _i * 8192), 16, 0, 0); } while (0)
; #define PG8_LDA(dst, b, h) do { _Pragma("unroll") for (int m = 0; m < 4; ++m) _Pragma("unroll") for (int k = 0; k < 2; ++k) dst[m][k] = *(const PG8_LAS bf16x8*)(lds + PG8_SA(b, h) + aoff + m * 2048 + k * 1024); } while (0)
; #define PG8_MMA(ai, bj, At, Bt) do { __builtin_amdgcn_s_setprio(1); _Pragma("unroll") for (int m = 0; m < 4; ++m) _Pragma("unroll") for (int n = 0; n < 2; ++n) _Pragma("unroll") for (int k = 0; k < 2; ++k) \
;         acc[ai][bj][m][n] = __builtin_amdgcn_mfma_f32_16x16x32_bf16(Bt[n][k], At[m][k], acc[ai][bj][m][n], 0, 0, 0); __builtin_amdgcn_s_setprio(0); } while (0)
; #define PG8_WAIT_V(n) asm volatile("s_waitcnt vmcnt(" #n ")" ::: "memory")
; #define PG8_WAIT_L(n) asm volatile("s_waitcnt lgkmcnt(" #n ")" ::: "memory")
; #define PG8_BAR __builtin_amdgcn_s_barrier()
; #define PG8_SCHED __builtin_amdgcn_sched_barrier(0)
; template <class Epi, class Sched, bool ALIGN_EPI = false, bool SP2 = false>
; __device__ __forceinline__ void gemm_phase(PG8_LAS unsigned char* lds, const Gemm g, const Sched& S, const Epi& E) {
;     ...
;             PG8_LDA(At, 1, 1); PG8_STAGE(PG8_SB(1, 0), b3, voffB); PG8_STAGE(PG8_SB(1, 1), b3 + hstep, voffB); PG8_STAGE(PG8_SA(1, 0), a3, voffA);
;             PG8_WAIT_V(8); PG8_WAIT_L(0); PG8_BAR; PG8_MMA(1, 0, At, B0); PG8_MMA(1, 1, At, B1); PG8_BAR; PG8_SCHED;
	s_add_i32 s34, s34, s17
	v_lshl_add_u64 v[200:201], v[200:201], 0, s[58:59]
	s_mov_b32 m0, s34
	ds_read_b128 v[176:179], v142 offset:49152
	ds_read_b128 v[184:187], v142 offset:50176
	ds_read_b128 v[188:191], v142 offset:51200
	ds_read_b128 v[192:195], v142 offset:52224
	ds_read_b128 v[196:199], v142 offset:53248
	ds_read_b128 v[210:213], v142 offset:54272
	ds_read_b128 v[214:217], v142 offset:55296
	ds_read_b128 v[218:221], v142 offset:56320
	global_load_lds_dwordx4 v[200:201], off
	v_lshl_add_u64 v[200:201], v[222:223], 0, s[58:59]
	s_add_i32 m0, s34, 0x2000
	s_add_i32 s34, s35, s17
	global_load_lds_dwordx4 v[200:201], off
	v_lshl_add_u64 v[200:201], v[224:225], 0, s[58:59]
	s_mov_b32 m0, s34
	s_nop 0
	global_load_lds_dwordx4 v[200:201], off
	v_lshl_add_u64 v[200:201], v[226:227], 0, s[58:59]
	s_add_i32 m0, s34, 0x2000
	s_nop 0
	global_load_lds_dwordx4 v[200:201], off
	v_lshl_add_u64 v[200:201], v[228:229], 0, s[58:59]
	s_mov_b32 m0, s22
	s_nop 0
	global_load_lds_dwordx4 v[200:201], off
	v_lshl_add_u64 v[200:201], v[230:231], 0, s[58:59]
	s_mov_b32 m0, s23
	s_nop 0
	global_load_lds_dwordx4 v[200:201], off
	s_waitcnt vmcnt(8)
	s_waitcnt lgkmcnt(0)
	s_barrier
	s_waitcnt lgkmcnt(0)
	v_mfma_f32_16x16x32_bf16 v[60:63], v[144:147], v[176:179], v[60:63]
	v_mfma_f32_16x16x32_bf16 v[56:59], v[152:155], v[176:179], v[56:59]
	v_mfma_f32_16x16x32_bf16 v[44:47], v[144:147], v[188:191], v[44:47]
	v_mfma_f32_16x16x32_bf16 v[40:43], v[152:155], v[188:191], v[40:43]
	v_mfma_f32_16x16x32_bf16 v[28:31], v[144:147], v[196:199], v[28:31]
	v_mfma_f32_16x16x32_bf16 v[24:27], v[152:155], v[196:199], v[24:27]
	v_mfma_f32_16x16x32_bf16 v[12:15], v[144:147], v[214:217], v[12:15]
	v_mfma_f32_16x16x32_bf16 v[8:11], v[152:155], v[214:217], v[8:11]
	v_mfma_f32_16x16x32_bf16 v[60:63], v[148:151], v[184:187], v[60:63]
	v_mfma_f32_16x16x32_bf16 v[56:59], v[156:159], v[184:187], v[56:59]
	v_mfma_f32_16x16x32_bf16 v[44:47], v[148:151], v[192:195], v[44:47]
	v_mfma_f32_16x16x32_bf16 v[40:43], v[156:159], v[192:195], v[40:43]
	v_mfma_f32_16x16x32_bf16 v[28:31], v[148:151], v[210:213], v[28:31]
	v_mfma_f32_16x16x32_bf16 v[24:27], v[156:159], v[210:213], v[24:27]
	v_mfma_f32_16x16x32_bf16 v[12:15], v[148:151], v[218:221], v[12:15]
	v_mfma_f32_16x16x32_bf16 v[8:11], v[156:159], v[218:221], v[8:11]
	v_mfma_f32_16x16x32_bf16 v[52:55], v[160:163], v[176:179], v[52:55]
	v_mfma_f32_16x16x32_bf16 v[48:51], v[168:171], v[176:179], v[48:51]
	v_mfma_f32_16x16x32_bf16 v[36:39], v[160:163], v[188:191], v[36:39]
	v_mfma_f32_16x16x32_bf16 v[32:35], v[168:171], v[188:191], v[32:35]
	v_mfma_f32_16x16x32_bf16 v[20:23], v[160:163], v[196:199], v[20:23]
	v_mfma_f32_16x16x32_bf16 v[16:19], v[168:171], v[196:199], v[16:19]
	v_mfma_f32_16x16x32_bf16 v[4:7], v[160:163], v[214:217], v[4:7]
	v_mfma_f32_16x16x32_bf16 v[0:3], v[168:171], v[214:217], v[0:3]
	v_mfma_f32_16x16x32_bf16 v[52:55], v[164:167], v[184:187], v[52:55]
	v_mfma_f32_16x16x32_bf16 v[48:51], v[172:175], v[184:187], v[48:51]
	v_mfma_f32_16x16x32_bf16 v[36:39], v[164:167], v[192:195], v[36:39]
	v_mfma_f32_16x16x32_bf16 v[32:35], v[172:175], v[192:195], v[32:35]
	v_mfma_f32_16x16x32_bf16 v[20:23], v[164:167], v[210:213], v[20:23]
	v_mfma_f32_16x16x32_bf16 v[16:19], v[172:175], v[210:213], v[16:19]
	v_mfma_f32_16x16x32_bf16 v[4:7], v[164:167], v[218:221], v[4:7]
	v_mfma_f32_16x16x32_bf16 v[0:3], v[172:175], v[218:221], v[0:3]
	s_barrier
	s_add_u32 s6, s6, 0x100
	s_addc_u32 s7, s7, 0
	s_add_u32 s53, s53, 0x100
	s_addc_u32 s60, s60, 0
	s_cmp_ge_i32 s61, s24
	s_mov_b32 s46, s61
	s_cbranch_scc0 .LBB0_481
	v_readlane_b32 s62, v252, 34
	v_readlane_b32 s64, v254, 51
	v_readlane_b32 s63, v252, 35
	v_readlane_b32 s65, v254, 52

; #define PG8_STAGE(bufoff, gbase, voff) do { _Pragma("unroll") for (int _i = 0; _i < 2; ++_i) \
;         __builtin_amdgcn_global_load_lds((const unsigned*)((const char*)(gbase) + (voff)[_i]), (PG8_LAS unsigned*)(lds + (bufoff) + ldsw + _i * 8192), 16, 0, 0); } while (0)
; #define PG8_LDA(dst, b, h) do { _Pragma("unroll") for (int m = 0; m < 4; ++m) _Pragma("unroll") for (int k = 0; k < 2; ++k) dst[m][k] = *(const PG8_LAS bf16x8*)(lds + PG8_SA(b, h) + aoff + m * 2048 + k * 1024); } while (0)
; #define PG8_LDB(dst, b, h) do { _Pragma("unroll") for (int n = 0; n < 2; ++n) _Pragma("unroll") for (int k = 0; k < 2; ++k) dst[n][k] = *(const PG8_LAS bf16x8*)(lds + PG8_SB(b, h) + boff + n * 2048 + k * 1024); } while (0)
; #define PG8_MMA(ai, bj, At, Bt) do { __builtin_amdgcn_s_setprio(1); _Pragma("unroll") for (int m = 0; m < 4; ++m) _Pragma("unroll") for (int n = 0; n < 2; ++n) _Pragma("unroll") for (int k = 0; k < 2; ++k) \
;         acc[ai][bj][m][n] = __builtin_amdgcn_mfma_f32_16x16x32_bf16(Bt[n][k], At[m][k], acc[ai][bj][m][n], 0, 0, 0); __builtin_amdgcn_s_setprio(0); } while (0)
; #define PG8_WAIT_V(n) asm volatile("s_waitcnt vmcnt(" #n ")" ::: "memory")
; #define PG8_WAIT_L(n) asm volatile("s_waitcnt lgkmcnt(" #n ")" ::: "memory")
; #define PG8_BAR __builtin_amdgcn_s_barrier()
; #define PG8_SCHED __builtin_amdgcn_sched_barrier(0)
; template <class Epi, class Sched, bool ALIGN_EPI = false, bool SP2 = false>
; __device__ __forceinline__ void gemm_phase(PG8_LAS unsigned char* lds, const Gemm g, const Sched& S, const Epi& E) {
;     ...
;             PG8_LDB(B0, 0, 0); PG8_LDB(B1, 0, 1); PG8_SCHED; PG8_LDA(At, 0, 0); PG8_STAGE(PG8_SA(1, 1), a1 + hstep, voffA);
;             PG8_WAIT_V(8); PG8_WAIT_L(0); PG8_BAR; PG8_MMA(0, 0, At, B0); PG8_MMA(0, 1, At, B1); PG8_BAR; PG8_SCHED;
;             PG8_LDA(At, 0, 1); PG8_STAGE(PG8_SB(0, 0), b2, voffB); PG8_STAGE(PG8_SB(0, 1), b2 + hstep, voffB); PG8_STAGE(PG8_SA(0, 0), a2, voffA);
;             PG8_WAIT_V(8); PG8_WAIT_L(0); PG8_BAR; PG8_MMA(1, 0, At, B0); PG8_MMA(1, 1, At, B1); PG8_BAR; PG8_SCHED;
.LBB0_505:
	s_add_i32 s24, s6, 2
	s_add_u32 s26, s4, 0x80
	s_addc_u32 s7, s5, 0
	s_add_i32 s34, 0, 0x10000
	s_cmp_eq_u32 s79, s6
	s_cselect_b32 s7, s73, s7
	s_cselect_b32 s6, s72, s26
	s_cselect_b32 s27, s31, s15
	s_cselect_b32 s26, s30, s13
	s_add_i32 s35, 0, 0x14000
	v_add_u32_e32 v154, s34, v179
	v_add_u32_e32 v170, s35, v179
	ds_read_b128 v[142:145], v154
	ds_read_b128 v[146:149], v154 offset:1024
	ds_read_b128 v[150:153], v154 offset:2048
	ds_read_b128 v[154:157], v154 offset:3072
	ds_read_b128 v[158:161], v170
	ds_read_b128 v[162:165], v170 offset:1024
	ds_read_b128 v[166:169], v170 offset:2048
	ds_read_b128 v[170:173], v170 offset:3072
	v_lshl_add_u64 v[240:241], s[4:5], 0, v[138:139]
	s_add_i32 m0, s75, 0xc000
	ds_read_b128 v[174:177], v201
	ds_read_b128 v[212:215], v201 offset:1024
	ds_read_b128 v[216:219], v201 offset:2048
	ds_read_b128 v[220:223], v201 offset:3072
	ds_read_b128 v[224:227], v201 offset:4096
	ds_read_b128 v[228:231], v201 offset:5120
	ds_read_b128 v[232:235], v201 offset:6144
	ds_read_b128 v[236:239], v201 offset:7168
	global_load_lds_dwordx4 v[240:241], off
	v_lshl_add_u64 v[240:241], s[4:5], 0, v[140:141]
	s_add_i32 m0, s75, 0xe000
	s_nop 0
	global_load_lds_dwordx4 v[240:241], off
	s_waitcnt vmcnt(8)
	s_waitcnt lgkmcnt(0)
	s_barrier
	s_waitcnt lgkmcnt(0)
	v_mfma_f32_16x16x32_bf16 v[116:119], v[142:145], v[174:177], v[116:119]
	v_mfma_f32_16x16x32_bf16 v[112:115], v[150:153], v[174:177], v[112:115]
	v_mfma_f32_16x16x32_bf16 v[108:111], v[142:145], v[216:219], v[108:111]
	v_mfma_f32_16x16x32_bf16 v[104:107], v[150:153], v[216:219], v[104:107]
	v_mfma_f32_16x16x32_bf16 v[92:95], v[142:145], v[224:227], v[92:95]
	v_mfma_f32_16x16x32_bf16 v[88:91], v[150:153], v[224:227], v[88:91]
	v_mfma_f32_16x16x32_bf16 v[76:79], v[142:145], v[232:235], v[76:79]
	v_mfma_f32_16x16x32_bf16 v[72:75], v[150:153], v[232:235], v[72:75]
	v_mfma_f32_16x16x32_bf16 v[116:119], v[146:149], v[212:215], v[116:119]
	v_mfma_f32_16x16x32_bf16 v[112:115], v[154:157], v[212:215], v[112:115]
	v_mfma_f32_16x16x32_bf16 v[108:111], v[146:149], v[220:223], v[108:111]
	v_mfma_f32_16x16x32_bf16 v[104:107], v[154:157], v[220:223], v[104:107]
	v_mfma_f32_16x16x32_bf16 v[92:95], v[146:149], v[228:231], v[92:95]
	v_mfma_f32_16x16x32_bf16 v[88:91], v[154:157], v[228:231], v[88:91]
	v_mfma_f32_16x16x32_bf16 v[76:79], v[146:149], v[236:239], v[76:79]
	v_mfma_f32_16x16x32_bf16 v[72:75], v[154:157], v[236:239], v[72:75]
	v_mfma_f32_16x16x32_bf16 v[124:127], v[158:161], v[174:177], v[124:127]
	v_mfma_f32_16x16x32_bf16 v[120:123], v[166:169], v[174:177], v[120:123]
	v_mfma_f32_16x16x32_bf16 v[100:103], v[158:161], v[216:219], v[100:103]
	v_mfma_f32_16x16x32_bf16 v[96:99], v[166:169], v[216:219], v[96:99]
	v_mfma_f32_16x16x32_bf16 v[84:87], v[158:161], v[224:227], v[84:87]
	v_mfma_f32_16x16x32_bf16 v[80:83], v[166:169], v[224:227], v[80:83]
	v_mfma_f32_16x16x32_bf16 v[68:71], v[158:161], v[232:235], v[68:71]
	v_mfma_f32_16x16x32_bf16 v[64:67], v[166:169], v[232:235], v[64:67]
	v_mfma_f32_16x16x32_bf16 v[124:127], v[162:165], v[212:215], v[124:127]
	v_mfma_f32_16x16x32_bf16 v[120:123], v[170:173], v[212:215], v[120:123]
	v_mfma_f32_16x16x32_bf16 v[100:103], v[162:165], v[220:223], v[100:103]
	v_mfma_f32_16x16x32_bf16 v[96:99], v[170:173], v[220:223], v[96:99]
	v_mfma_f32_16x16x32_bf16 v[84:87], v[162:165], v[228:231], v[84:87]
	v_mfma_f32_16x16x32_bf16 v[80:83], v[170:173], v[228:231], v[80:83]
	v_mfma_f32_16x16x32_bf16 v[68:71], v[162:165], v[236:239], v[68:71]
	v_mfma_f32_16x16x32_bf16 v[64:67], v[170:173], v[236:239], v[64:67]
	s_barrier
	s_add_i32 s34, s34, s19
	v_lshl_add_u64 v[240:241], s[26:27], 0, v[130:131]
	s_mov_b32 m0, s34
	ds_read_b128 v[174:177], v201 offset:16384
	ds_read_b128 v[212:215], v201 offset:17408
	ds_read_b128 v[216:219], v201 offset:18432
	ds_read_b128 v[220:223], v201 offset:19456
	ds_read_b128 v[224:227], v201 offset:20480
	ds_read_b128 v[228:231], v201 offset:21504
	ds_read_b128 v[232:235], v201 offset:22528
	ds_read_b128 v[236:239], v201 offset:23552
	global_load_lds_dwordx4 v[240:241], off
	s_add_i32 m0, s34, 0x2000
	v_lshl_add_u64 v[242:243], s[26:27], 0, v[134:135]
	s_add_u32 s26, s26, s40
	s_addc_u32 s27, s27, 0
	s_add_i32 s34, s35, s19
	global_load_lds_dwordx4 v[242:243], off
	v_lshl_add_u64 v[244:245], s[26:27], 0, v[130:131]
	s_mov_b32 m0, s34
	v_lshl_add_u64 v[246:247], s[26:27], 0, v[134:135]
	global_load_lds_dwordx4 v[244:245], off
	s_add_i32 m0, s34, 0x2000
	v_lshl_add_u64 v[248:249], s[6:7], 0, v[128:129]
	global_load_lds_dwordx4 v[246:247], off
	s_mov_b32 m0, s75
	v_lshl_add_u64 v[250:251], s[6:7], 0, v[132:133]
	global_load_lds_dwordx4 v[248:249], off
	s_mov_b32 m0, s76
	s_nop 0
	global_load_lds_dwordx4 v[250:251], off
	s_waitcnt vmcnt(8)
	s_waitcnt lgkmcnt(0)
	s_barrier
; #define PG8_STAGE(bufoff, gbase, voff) do { _Pragma("unroll") for (int _i = 0; _i < 2; ++_i) \
;         __builtin_amdgcn_global_load_lds((const unsigned*)((const char*)(gbase) + (voff)[_i]), (PG8_LAS unsigned*)(lds + (bufoff) + ldsw + _i * 8192), 16, 0, 0); } while (0)
; #define PG8_LDA(dst, b, h) do { _Pragma("unroll") for (int m = 0; m < 4; ++m) _Pragma("unroll") for (int k = 0; k < 2; ++k) dst[m][k] = *(const PG8_LAS bf16x8*)(lds + PG8_SA(b, h) + aoff + m * 2048 + k * 1024); } while (0)
; #define PG8_LDB(dst, b, h) do { _Pragma("unroll") for (int n = 0; n < 2; ++n) _Pragma("unroll") for (int k = 0; k < 2; ++k) dst[n][k] = *(const PG8_LAS bf16x8*)(lds + PG8_SB(b, h) + boff + n * 2048 + k * 1024); } while (0)
; #define PG8_MMA(ai, bj, At, Bt) do { __builtin_amdgcn_s_setprio(1); _Pragma("unroll") for (int m = 0; m < 4; ++m) _Pragma("unroll") for (int n = 0; n < 2; ++n) _Pragma("unroll") for (int k = 0; k < 2; ++k) \
;         acc[ai][bj][m][n] = __builtin_amdgcn_mfma_f32_16x16x32_bf16(Bt[n][k], At[m][k], acc[ai][bj][m][n], 0, 0, 0); __builtin_amdgcn_s_setprio(0); } while (0)
; #define PG8_WAIT_V(n) asm volatile("s_waitcnt vmcnt(" #n ")" ::: "memory")
; #define PG8_WAIT_L(n) asm volatile("s_waitcnt lgkmcnt(" #n ")" ::: "memory")
; #define PG8_BAR __builtin_amdgcn_s_barrier()
; #define PG8_SCHED __builtin_amdgcn_sched_barrier(0)
; template <class Epi, class Sched, bool ALIGN_EPI = false, bool SP2 = false>
; __device__ __forceinline__ void gemm_phase(PG8_LAS unsigned char* lds, const Gemm g, const Sched& S, const Epi& E) {
;     ...
;             PG8_WAIT_V(8); PG8_WAIT_L(0); PG8_BAR; PG8_MMA(1, 0, At, B0); PG8_MMA(1, 1, At, B1); PG8_BAR; PG8_SCHED;
;             PG8_LDB(B0, 1, 0); PG8_LDB(B1, 1, 1); PG8_SCHED; PG8_LDA(At, 1, 0); PG8_STAGE(PG8_SA(0, 1), a2 + hstep, voffA);
;             PG8_WAIT_V(8); PG8_WAIT_L(0); PG8_BAR; PG8_MMA(0, 0, At, B0); PG8_MMA(0, 1, At, B1); PG8_BAR; PG8_SCHED;
;             PG8_LDA(At, 1, 1); PG8_STAGE(PG8_SB(1, 0), b3, voffB); PG8_STAGE(PG8_SB(1, 1), b3 + hstep, voffB); PG8_STAGE(PG8_SA(1, 0), a3, voffA);
	s_waitcnt lgkmcnt(0)
	v_mfma_f32_16x16x32_bf16 v[60:63], v[142:145], v[174:177], v[60:63]
	v_mfma_f32_16x16x32_bf16 v[56:59], v[150:153], v[174:177], v[56:59]
	v_mfma_f32_16x16x32_bf16 v[44:47], v[142:145], v[216:219], v[44:47]
	v_mfma_f32_16x16x32_bf16 v[40:43], v[150:153], v[216:219], v[40:43]
	v_mfma_f32_16x16x32_bf16 v[28:31], v[142:145], v[224:227], v[28:31]
	v_mfma_f32_16x16x32_bf16 v[24:27], v[150:153], v[224:227], v[24:27]
	v_mfma_f32_16x16x32_bf16 v[12:15], v[142:145], v[232:235], v[12:15]
	v_mfma_f32_16x16x32_bf16 v[8:11], v[150:153], v[232:235], v[8:11]
	v_mfma_f32_16x16x32_bf16 v[60:63], v[146:149], v[212:215], v[60:63]
	v_mfma_f32_16x16x32_bf16 v[56:59], v[154:157], v[212:215], v[56:59]
	v_mfma_f32_16x16x32_bf16 v[44:47], v[146:149], v[220:223], v[44:47]
	v_mfma_f32_16x16x32_bf16 v[40:43], v[154:157], v[220:223], v[40:43]
	v_mfma_f32_16x16x32_bf16 v[28:31], v[146:149], v[228:231], v[28:31]
	v_mfma_f32_16x16x32_bf16 v[24:27], v[154:157], v[228:231], v[24:27]
	v_mfma_f32_16x16x32_bf16 v[12:15], v[146:149], v[236:239], v[12:15]
	v_mfma_f32_16x16x32_bf16 v[8:11], v[154:157], v[236:239], v[8:11]
	v_mfma_f32_16x16x32_bf16 v[52:55], v[158:161], v[174:177], v[52:55]
	v_mfma_f32_16x16x32_bf16 v[48:51], v[166:169], v[174:177], v[48:51]
	v_mfma_f32_16x16x32_bf16 v[36:39], v[158:161], v[216:219], v[36:39]
	v_mfma_f32_16x16x32_bf16 v[32:35], v[166:169], v[216:219], v[32:35]
	v_mfma_f32_16x16x32_bf16 v[20:23], v[158:161], v[224:227], v[20:23]
	v_mfma_f32_16x16x32_bf16 v[16:19], v[166:169], v[224:227], v[16:19]
	v_mfma_f32_16x16x32_bf16 v[4:7], v[158:161], v[232:235], v[4:7]
	v_mfma_f32_16x16x32_bf16 v[0:3], v[166:169], v[232:235], v[0:3]
	v_mfma_f32_16x16x32_bf16 v[52:55], v[162:165], v[212:215], v[52:55]
	v_mfma_f32_16x16x32_bf16 v[48:51], v[170:173], v[212:215], v[48:51]
	v_mfma_f32_16x16x32_bf16 v[36:39], v[162:165], v[220:223], v[36:39]
	v_mfma_f32_16x16x32_bf16 v[32:35], v[170:173], v[220:223], v[32:35]
	v_mfma_f32_16x16x32_bf16 v[20:23], v[162:165], v[228:231], v[20:23]
	v_mfma_f32_16x16x32_bf16 v[16:19], v[170:173], v[228:231], v[16:19]
	v_mfma_f32_16x16x32_bf16 v[4:7], v[162:165], v[236:239], v[4:7]
	v_mfma_f32_16x16x32_bf16 v[0:3], v[170:173], v[236:239], v[0:3]
	s_barrier
	s_add_i32 s26, 0, 0x18000
	s_add_i32 s27, 0, 0x1c000
	v_add_u32_e32 v154, s26, v179
	v_add_u32_e32 v170, s27, v179
	ds_read_b128 v[142:145], v154
	ds_read_b128 v[146:149], v154 offset:1024
	ds_read_b128 v[150:153], v154 offset:2048
	ds_read_b128 v[154:157], v154 offset:3072
	ds_read_b128 v[158:161], v170
	ds_read_b128 v[162:165], v170 offset:1024
	ds_read_b128 v[166:169], v170 offset:2048
	ds_read_b128 v[170:173], v170 offset:3072
	s_add_u32 s6, s6, s40
	s_addc_u32 s7, s7, 0
	s_mov_b32 m0, s77
	v_lshl_add_u64 v[210:211], s[6:7], 0, v[128:129]
	ds_read_b128 v[174:177], v201 offset:32768
	ds_read_b128 v[212:215], v201 offset:33792
	ds_read_b128 v[216:219], v201 offset:34816
	ds_read_b128 v[220:223], v201 offset:35840
	ds_read_b128 v[224:227], v201 offset:36864
	ds_read_b128 v[228:231], v201 offset:37888
	ds_read_b128 v[232:235], v201 offset:38912
	ds_read_b128 v[236:239], v201 offset:39936
	global_load_lds_dwordx4 v[210:211], off
	v_lshl_add_u64 v[210:211], s[6:7], 0, v[132:133]
	s_mov_b32 m0, s78
	s_nop 0
	global_load_lds_dwordx4 v[210:211], off
	s_waitcnt vmcnt(8)
	s_waitcnt lgkmcnt(0)
	s_barrier
	s_waitcnt lgkmcnt(0)
	v_mfma_f32_16x16x32_bf16 v[116:119], v[142:145], v[174:177], v[116:119]
	v_mfma_f32_16x16x32_bf16 v[112:115], v[150:153], v[174:177], v[112:115]
	v_mfma_f32_16x16x32_bf16 v[108:111], v[142:145], v[216:219], v[108:111]
	v_mfma_f32_16x16x32_bf16 v[104:107], v[150:153], v[216:219], v[104:107]
	v_mfma_f32_16x16x32_bf16 v[92:95], v[142:145], v[224:227], v[92:95]
	v_mfma_f32_16x16x32_bf16 v[88:91], v[150:153], v[224:227], v[88:91]
	v_mfma_f32_16x16x32_bf16 v[76:79], v[142:145], v[232:235], v[76:79]
	v_mfma_f32_16x16x32_bf16 v[72:75], v[150:153], v[232:235], v[72:75]
	v_mfma_f32_16x16x32_bf16 v[116:119], v[146:149], v[212:215], v[116:119]
	v_mfma_f32_16x16x32_bf16 v[112:115], v[154:157], v[212:215], v[112:115]
	v_mfma_f32_16x16x32_bf16 v[108:111], v[146:149], v[220:223], v[108:111]
	v_mfma_f32_16x16x32_bf16 v[104:107], v[154:157], v[220:223], v[104:107]
	v_mfma_f32_16x16x32_bf16 v[92:95], v[146:149], v[228:231], v[92:95]
	v_mfma_f32_16x16x32_bf16 v[88:91], v[154:157], v[228:231], v[88:91]
	v_mfma_f32_16x16x32_bf16 v[76:79], v[146:149], v[236:239], v[76:79]
	v_mfma_f32_16x16x32_bf16 v[72:75], v[154:157], v[236:239], v[72:75]
	v_mfma_f32_16x16x32_bf16 v[124:127], v[158:161], v[174:177], v[124:127]
	v_mfma_f32_16x16x32_bf16 v[120:123], v[166:169], v[174:177], v[120:123]
	v_mfma_f32_16x16x32_bf16 v[100:103], v[158:161], v[216:219], v[100:103]
	v_mfma_f32_16x16x32_bf16 v[96:99], v[166:169], v[216:219], v[96:99]
	v_mfma_f32_16x16x32_bf16 v[84:87], v[158:161], v[224:227], v[84:87]
	v_mfma_f32_16x16x32_bf16 v[80:83], v[166:169], v[224:227], v[80:83]
	v_mfma_f32_16x16x32_bf16 v[68:71], v[158:161], v[232:235], v[68:71]
	v_mfma_f32_16x16x32_bf16 v[64:67], v[166:169], v[232:235], v[64:67]
	v_mfma_f32_16x16x32_bf16 v[124:127], v[162:165], v[212:215], v[124:127]
	v_mfma_f32_16x16x32_bf16 v[120:123], v[170:173], v[212:215], v[120:123]
	v_mfma_f32_16x16x32_bf16 v[100:103], v[162:165], v[220:223], v[100:103]
	v_mfma_f32_16x16x32_bf16 v[96:99], v[170:173], v[220:223], v[96:99]
	v_mfma_f32_16x16x32_bf16 v[84:87], v[162:165], v[228:231], v[84:87]
	v_mfma_f32_16x16x32_bf16 v[80:83], v[170:173], v[228:231], v[80:83]
	v_mfma_f32_16x16x32_bf16 v[68:71], v[162:165], v[236:239], v[68:71]
	v_mfma_f32_16x16x32_bf16 v[64:67], v[170:173], v[236:239], v[64:67]
	s_barrier
; #define PG8_STAGE(bufoff, gbase, voff) do { _Pragma("unroll") for (int _i = 0; _i < 2; ++_i) \
;         __builtin_amdgcn_global_load_lds((const unsigned*)((const char*)(gbase) + (voff)[_i]), (PG8_LAS unsigned*)(lds + (bufoff) + ldsw + _i * 8192), 16, 0, 0); } while (0)
; #define PG8_LDA(dst, b, h) do { _Pragma("unroll") for (int m = 0; m < 4; ++m) _Pragma("unroll") for (int k = 0; k < 2; ++k) dst[m][k] = *(const PG8_LAS bf16x8*)(lds + PG8_SA(b, h) + aoff + m * 2048 + k * 1024); } while (0)
; #define PG8_MMA(ai, bj, At, Bt) do { __builtin_amdgcn_s_setprio(1); _Pragma("unroll") for (int m = 0; m < 4; ++m) _Pragma("unroll") for (int n = 0; n < 2; ++n) _Pragma("unroll") for (int k = 0; k < 2; ++k) \
;         acc[ai][bj][m][n] = __builtin_amdgcn_mfma_f32_16x16x32_bf16(Bt[n][k], At[m][k], acc[ai][bj][m][n], 0, 0, 0); __builtin_amdgcn_s_setprio(0); } while (0)
; #define PG8_WAIT_V(n) asm volatile("s_waitcnt vmcnt(" #n ")" ::: "memory")
; #define PG8_WAIT_L(n) asm volatile("s_waitcnt lgkmcnt(" #n ")" ::: "memory")
; #define PG8_BAR __builtin_amdgcn_s_barrier()
; #define PG8_SCHED __builtin_amdgcn_sched_barrier(0)
; template <class Epi, class Sched, bool ALIGN_EPI = false, bool SP2 = false>
; __device__ __forceinline__ void gemm_phase(PG8_LAS unsigned char* lds, const Gemm g, const Sched& S, const Epi& E) {
;     ...
;             PG8_LDA(At, 1, 1); PG8_STAGE(PG8_SB(1, 0), b3, voffB); PG8_STAGE(PG8_SB(1, 1), b3 + hstep, voffB); PG8_STAGE(PG8_SA(1, 0), a3, voffA);
;             PG8_WAIT_V(8); PG8_WAIT_L(0); PG8_BAR; PG8_MMA(1, 0, At, B0); PG8_MMA(1, 1, At, B1); PG8_BAR; PG8_SCHED;
	s_add_i32 s6, s26, s19
	v_lshl_add_u64 v[210:211], v[240:241], 0, s[58:59]
	s_mov_b32 m0, s6
	ds_read_b128 v[174:177], v201 offset:49152
	ds_read_b128 v[212:215], v201 offset:50176
	ds_read_b128 v[216:219], v201 offset:51200
	ds_read_b128 v[220:223], v201 offset:52224
	ds_read_b128 v[224:227], v201 offset:53248
	ds_read_b128 v[228:231], v201 offset:54272
	ds_read_b128 v[232:235], v201 offset:55296
	ds_read_b128 v[236:239], v201 offset:56320
	global_load_lds_dwordx4 v[210:211], off
	v_lshl_add_u64 v[210:211], v[242:243], 0, s[58:59]
	s_add_i32 m0, s6, 0x2000
	s_add_i32 s6, s27, s19
	global_load_lds_dwordx4 v[210:211], off
	v_lshl_add_u64 v[210:211], v[244:245], 0, s[58:59]
	s_mov_b32 m0, s6
	s_nop 0
	global_load_lds_dwordx4 v[210:211], off
	v_lshl_add_u64 v[210:211], v[246:247], 0, s[58:59]
	s_add_i32 m0, s6, 0x2000
	s_nop 0
	global_load_lds_dwordx4 v[210:211], off
	v_lshl_add_u64 v[210:211], v[248:249], 0, s[58:59]
	s_mov_b32 m0, s96
	s_nop 0
	global_load_lds_dwordx4 v[210:211], off
	v_lshl_add_u64 v[210:211], v[250:251], 0, s[58:59]
	s_mov_b32 m0, s97
	s_nop 0
	global_load_lds_dwordx4 v[210:211], off
	s_waitcnt vmcnt(8)
	s_waitcnt lgkmcnt(0)
	s_barrier
	s_waitcnt lgkmcnt(0)
	v_mfma_f32_16x16x32_bf16 v[60:63], v[142:145], v[174:177], v[60:63]
	v_mfma_f32_16x16x32_bf16 v[56:59], v[150:153], v[174:177], v[56:59]
	v_mfma_f32_16x16x32_bf16 v[44:47], v[142:145], v[216:219], v[44:47]
	v_mfma_f32_16x16x32_bf16 v[40:43], v[150:153], v[216:219], v[40:43]
	v_mfma_f32_16x16x32_bf16 v[28:31], v[142:145], v[224:227], v[28:31]
	v_mfma_f32_16x16x32_bf16 v[24:27], v[150:153], v[224:227], v[24:27]
	v_mfma_f32_16x16x32_bf16 v[12:15], v[142:145], v[232:235], v[12:15]
	v_mfma_f32_16x16x32_bf16 v[8:11], v[150:153], v[232:235], v[8:11]
	v_mfma_f32_16x16x32_bf16 v[60:63], v[146:149], v[212:215], v[60:63]
	v_mfma_f32_16x16x32_bf16 v[56:59], v[154:157], v[212:215], v[56:59]
	v_mfma_f32_16x16x32_bf16 v[44:47], v[146:149], v[220:223], v[44:47]
	v_mfma_f32_16x16x32_bf16 v[40:43], v[154:157], v[220:223], v[40:43]
	v_mfma_f32_16x16x32_bf16 v[28:31], v[146:149], v[228:231], v[28:31]
	v_mfma_f32_16x16x32_bf16 v[24:27], v[154:157], v[228:231], v[24:27]
	v_mfma_f32_16x16x32_bf16 v[12:15], v[146:149], v[236:239], v[12:15]
	v_mfma_f32_16x16x32_bf16 v[8:11], v[154:157], v[236:239], v[8:11]
	v_mfma_f32_16x16x32_bf16 v[52:55], v[158:161], v[174:177], v[52:55]
	v_mfma_f32_16x16x32_bf16 v[48:51], v[166:169], v[174:177], v[48:51]
	v_mfma_f32_16x16x32_bf16 v[36:39], v[158:161], v[216:219], v[36:39]
	v_mfma_f32_16x16x32_bf16 v[32:35], v[166:169], v[216:219], v[32:35]
	v_mfma_f32_16x16x32_bf16 v[20:23], v[158:161], v[224:227], v[20:23]
	v_mfma_f32_16x16x32_bf16 v[16:19], v[166:169], v[224:227], v[16:19]
	v_mfma_f32_16x16x32_bf16 v[4:7], v[158:161], v[232:235], v[4:7]
	v_mfma_f32_16x16x32_bf16 v[0:3], v[166:169], v[232:235], v[0:3]
	v_mfma_f32_16x16x32_bf16 v[52:55], v[162:165], v[212:215], v[52:55]
	v_mfma_f32_16x16x32_bf16 v[48:51], v[170:173], v[212:215], v[48:51]
	v_mfma_f32_16x16x32_bf16 v[36:39], v[162:165], v[220:223], v[36:39]
	v_mfma_f32_16x16x32_bf16 v[32:35], v[170:173], v[220:223], v[32:35]
	v_mfma_f32_16x16x32_bf16 v[20:23], v[162:165], v[228:231], v[20:23]
	v_mfma_f32_16x16x32_bf16 v[16:19], v[170:173], v[228:231], v[16:19]
	v_mfma_f32_16x16x32_bf16 v[4:7], v[162:165], v[236:239], v[4:7]
	v_mfma_f32_16x16x32_bf16 v[0:3], v[170:173], v[236:239], v[0:3]
	s_barrier
	s_add_u32 s4, s4, 0x100
	s_addc_u32 s5, s5, 0
	s_add_u32 s13, s13, 0x100
	s_addc_u32 s15, s15, 0
	s_cmp_ge_u32 s24, s74
	s_mov_b32 s6, s24
	s_cbranch_scc0 .LBB0_505
	v_readlane_b32 s4, v255, 4
	v_readlane_b32 s5, v255, 5
	s_and_b64 vcc, exec, s[4:5]
	s_cbranch_vccz .LBB0_508
	s_barrier

; #define PG8_STAGE(bufoff, gbase, voff) do { _Pragma("unroll") for (int _i = 0; _i < 2; ++_i) \
;         __builtin_amdgcn_global_load_lds((const unsigned*)((const char*)(gbase) + (voff)[_i]), (PG8_LAS unsigned*)(lds + (bufoff) + ldsw + _i * 8192), 16, 0, 0); } while (0)
; #define PG8_LDA(dst, b, h) do { _Pragma("unroll") for (int m = 0; m < 4; ++m) _Pragma("unroll") for (int k = 0; k < 2; ++k) dst[m][k] = *(const PG8_LAS bf16x8*)(lds + PG8_SA(b, h) + aoff + m * 2048 + k * 1024); } while (0)
; #define PG8_LDB(dst, b, h) do { _Pragma("unroll") for (int n = 0; n < 2; ++n) _Pragma("unroll") for (int k = 0; k < 2; ++k) dst[n][k] = *(const PG8_LAS bf16x8*)(lds + PG8_SB(b, h) + boff + n * 2048 + k * 1024); } while (0)
; #define PG8_MMA(ai, bj, At, Bt) do { __builtin_amdgcn_s_setprio(1); _Pragma("unroll") for (int m = 0; m < 4; ++m) _Pragma("unroll") for (int n = 0; n < 2; ++n) _Pragma("unroll") for (int k = 0; k < 2; ++k) \
;         acc[ai][bj][m][n] = __builtin_amdgcn_mfma_f32_16x16x32_bf16(Bt[n][k], At[m][k], acc[ai][bj][m][n], 0, 0, 0); __builtin_amdgcn_s_setprio(0); } while (0)
; #define PG8_WAIT_V(n) asm volatile("s_waitcnt vmcnt(" #n ")" ::: "memory")
; #define PG8_WAIT_L(n) asm volatile("s_waitcnt lgkmcnt(" #n ")" ::: "memory")
; #define PG8_BAR __builtin_amdgcn_s_barrier()
; #define PG8_SCHED __builtin_amdgcn_sched_barrier(0)
; template <class Epi, class Sched, bool ALIGN_EPI = false, bool SP2 = false>
; __device__ __forceinline__ void gemm_phase(PG8_LAS unsigned char* lds, const Gemm g, const Sched& S, const Epi& E) {
;     ...
;             PG8_LDB(B0, 0, 0); PG8_LDB(B1, 0, 1); PG8_SCHED; PG8_LDA(At, 0, 0); PG8_STAGE(PG8_SA(1, 1), a1 + hstep, voffA);
;             PG8_WAIT_V(8); PG8_WAIT_L(0); PG8_BAR; PG8_MMA(0, 0, At, B0); PG8_MMA(0, 1, At, B1); PG8_BAR; PG8_SCHED;
;             PG8_LDA(At, 0, 1); PG8_STAGE(PG8_SB(0, 0), b2, voffB); PG8_STAGE(PG8_SB(0, 1), b2 + hstep, voffB); PG8_STAGE(PG8_SA(0, 0), a2, voffA);
;             PG8_WAIT_V(8); PG8_WAIT_L(0); PG8_BAR; PG8_MMA(1, 0, At, B0); PG8_MMA(1, 1, At, B1); PG8_BAR; PG8_SCHED;
.LBB0_890:
	s_add_i32 s97, s42, 2
	s_add_u32 s34, s6, 0x80
	s_addc_u32 s35, s7, 0
	s_add_i32 s16, 0, 0x10000
	s_cmp_eq_u32 s13, s42
	s_cselect_b32 s43, s45, s35
	s_cselect_b32 s42, s46, s34
	s_cselect_b32 vcc_hi, s47, s79
	s_cselect_b32 vcc_lo, s49, s50
	s_add_i32 s34, 0, 0x14000
	v_add_u32_e32 v140, s16, v210
	v_add_u32_e32 v156, s34, v210
	ds_read_b128 v[128:131], v140
	ds_read_b128 v[132:135], v140 offset:1024
	ds_read_b128 v[136:139], v140 offset:2048
	ds_read_b128 v[140:143], v140 offset:3072
	ds_read_b128 v[144:147], v156
	ds_read_b128 v[148:151], v156 offset:1024
	ds_read_b128 v[152:155], v156 offset:2048
	ds_read_b128 v[156:159], v156 offset:3072
	v_lshl_add_u64 v[178:179], s[6:7], 0, v[170:171]
	s_add_i32 m0, s19, 0xc000
	ds_read_b128 v[174:177], v215
	ds_read_b128 v[184:187], v215 offset:1024
	ds_read_b128 v[188:191], v215 offset:2048
	ds_read_b128 v[192:195], v215 offset:3072
	ds_read_b128 v[196:199], v215 offset:4096
	ds_read_b128 v[216:219], v215 offset:5120
	ds_read_b128 v[220:223], v215 offset:6144
	ds_read_b128 v[224:227], v215 offset:7168
	global_load_lds_dwordx4 v[178:179], off
	v_lshl_add_u64 v[178:179], s[6:7], 0, v[172:173]
	s_add_i32 m0, s19, 0xe000
	s_nop 0
	global_load_lds_dwordx4 v[178:179], off
	s_waitcnt vmcnt(8)
	s_waitcnt lgkmcnt(0)
	s_barrier
	s_waitcnt lgkmcnt(0)
	v_mfma_f32_16x16x32_bf16 v[124:127], v[128:131], v[174:177], v[124:127]
	v_mfma_f32_16x16x32_bf16 v[120:123], v[136:139], v[174:177], v[120:123]
	v_mfma_f32_16x16x32_bf16 v[108:111], v[128:131], v[188:191], v[108:111]
	v_mfma_f32_16x16x32_bf16 v[104:107], v[136:139], v[188:191], v[104:107]
	v_mfma_f32_16x16x32_bf16 v[92:95], v[128:131], v[196:199], v[92:95]
	v_mfma_f32_16x16x32_bf16 v[88:91], v[136:139], v[196:199], v[88:91]
	v_mfma_f32_16x16x32_bf16 v[76:79], v[128:131], v[220:223], v[76:79]
	v_mfma_f32_16x16x32_bf16 v[72:75], v[136:139], v[220:223], v[72:75]
	v_mfma_f32_16x16x32_bf16 v[124:127], v[132:135], v[184:187], v[124:127]
	v_mfma_f32_16x16x32_bf16 v[120:123], v[140:143], v[184:187], v[120:123]
	v_mfma_f32_16x16x32_bf16 v[108:111], v[132:135], v[192:195], v[108:111]
	v_mfma_f32_16x16x32_bf16 v[104:107], v[140:143], v[192:195], v[104:107]
	v_mfma_f32_16x16x32_bf16 v[92:95], v[132:135], v[216:219], v[92:95]
	v_mfma_f32_16x16x32_bf16 v[88:91], v[140:143], v[216:219], v[88:91]
	v_mfma_f32_16x16x32_bf16 v[76:79], v[132:135], v[224:227], v[76:79]
	v_mfma_f32_16x16x32_bf16 v[72:75], v[140:143], v[224:227], v[72:75]
	v_mfma_f32_16x16x32_bf16 v[116:119], v[144:147], v[174:177], v[116:119]
	v_mfma_f32_16x16x32_bf16 v[112:115], v[152:155], v[174:177], v[112:115]
	v_mfma_f32_16x16x32_bf16 v[100:103], v[144:147], v[188:191], v[100:103]
	v_mfma_f32_16x16x32_bf16 v[96:99], v[152:155], v[188:191], v[96:99]
	v_mfma_f32_16x16x32_bf16 v[84:87], v[144:147], v[196:199], v[84:87]
	v_mfma_f32_16x16x32_bf16 v[80:83], v[152:155], v[196:199], v[80:83]
	v_mfma_f32_16x16x32_bf16 v[68:71], v[144:147], v[220:223], v[68:71]
	v_mfma_f32_16x16x32_bf16 v[64:67], v[152:155], v[220:223], v[64:67]
	v_mfma_f32_16x16x32_bf16 v[116:119], v[148:151], v[184:187], v[116:119]
	v_mfma_f32_16x16x32_bf16 v[112:115], v[156:159], v[184:187], v[112:115]
	v_mfma_f32_16x16x32_bf16 v[100:103], v[148:151], v[192:195], v[100:103]
	v_mfma_f32_16x16x32_bf16 v[96:99], v[156:159], v[192:195], v[96:99]
	v_mfma_f32_16x16x32_bf16 v[84:87], v[148:151], v[216:219], v[84:87]
	v_mfma_f32_16x16x32_bf16 v[80:83], v[156:159], v[216:219], v[80:83]
	v_mfma_f32_16x16x32_bf16 v[68:71], v[148:151], v[224:227], v[68:71]
	v_mfma_f32_16x16x32_bf16 v[64:67], v[156:159], v[224:227], v[64:67]
	s_barrier
	s_add_i32 s16, s16, s24
	v_lshl_add_u64 v[178:179], vcc, 0, v[180:181]
	s_mov_b32 m0, s16
	ds_read_b128 v[174:177], v215 offset:16384
	ds_read_b128 v[184:187], v215 offset:17408
	ds_read_b128 v[188:191], v215 offset:18432
	ds_read_b128 v[192:195], v215 offset:19456
	ds_read_b128 v[196:199], v215 offset:20480
	ds_read_b128 v[216:219], v215 offset:21504
	ds_read_b128 v[220:223], v215 offset:22528
	ds_read_b128 v[224:227], v215 offset:23552
	global_load_lds_dwordx4 v[178:179], off
	s_add_i32 m0, s16, 0x2000
	v_lshl_add_u64 v[200:201], vcc, 0, v[160:161]
	s_add_u32 vcc_lo, vcc_lo, s48
	s_addc_u32 vcc_hi, vcc_hi, 0
	s_add_i32 s16, s34, s24
	global_load_lds_dwordx4 v[200:201], off
	v_lshl_add_u64 v[228:229], vcc, 0, v[180:181]
	s_mov_b32 m0, s16
	v_lshl_add_u64 v[230:231], vcc, 0, v[160:161]
	global_load_lds_dwordx4 v[228:229], off
	s_add_i32 m0, s16, 0x2000
	v_lshl_add_u64 v[232:233], s[42:43], 0, v[164:165]
	global_load_lds_dwordx4 v[230:231], off
	s_mov_b32 m0, s19
	v_lshl_add_u64 v[234:235], s[42:43], 0, v[162:163]
	global_load_lds_dwordx4 v[232:233], off
	s_mov_b32 m0, s85
	s_nop 0
	global_load_lds_dwordx4 v[234:235], off
	s_waitcnt vmcnt(8)
	s_waitcnt lgkmcnt(0)
	s_barrier
; #define PG8_STAGE(bufoff, gbase, voff) do { _Pragma("unroll") for (int _i = 0; _i < 2; ++_i) \
;         __builtin_amdgcn_global_load_lds((const unsigned*)((const char*)(gbase) + (voff)[_i]), (PG8_LAS unsigned*)(lds + (bufoff) + ldsw + _i * 8192), 16, 0, 0); } while (0)
; #define PG8_LDA(dst, b, h) do { _Pragma("unroll") for (int m = 0; m < 4; ++m) _Pragma("unroll") for (int k = 0; k < 2; ++k) dst[m][k] = *(const PG8_LAS bf16x8*)(lds + PG8_SA(b, h) + aoff + m * 2048 + k * 1024); } while (0)
; #define PG8_LDB(dst, b, h) do { _Pragma("unroll") for (int n = 0; n < 2; ++n) _Pragma("unroll") for (int k = 0; k < 2; ++k) dst[n][k] = *(const PG8_LAS bf16x8*)(lds + PG8_SB(b, h) + boff + n * 2048 + k * 1024); } while (0)
; #define PG8_MMA(ai, bj, At, Bt) do { __builtin_amdgcn_s_setprio(1); _Pragma("unroll") for (int m = 0; m < 4; ++m) _Pragma("unroll") for (int n = 0; n < 2; ++n) _Pragma("unroll") for (int k = 0; k < 2; ++k) \
;         acc[ai][bj][m][n] = __builtin_amdgcn_mfma_f32_16x16x32_bf16(Bt[n][k], At[m][k], acc[ai][bj][m][n], 0, 0, 0); __builtin_amdgcn_s_setprio(0); } while (0)
; #define PG8_WAIT_V(n) asm volatile("s_waitcnt vmcnt(" #n ")" ::: "memory")
; #define PG8_WAIT_L(n) asm volatile("s_waitcnt lgkmcnt(" #n ")" ::: "memory")
; #define PG8_BAR __builtin_amdgcn_s_barrier()
; #define PG8_SCHED __builtin_amdgcn_sched_barrier(0)
; template <class Epi, class Sched, bool ALIGN_EPI = false, bool SP2 = false>
; __device__ __forceinline__ void gemm_phase(PG8_LAS unsigned char* lds, const Gemm g, const Sched& S, const Epi& E) {
;     ...
;             PG8_WAIT_V(8); PG8_WAIT_L(0); PG8_BAR; PG8_MMA(1, 0, At, B0); PG8_MMA(1, 1, At, B1); PG8_BAR; PG8_SCHED;
;             PG8_LDB(B0, 1, 0); PG8_LDB(B1, 1, 1); PG8_SCHED; PG8_LDA(At, 1, 0); PG8_STAGE(PG8_SA(0, 1), a2 + hstep, voffA);
;             PG8_WAIT_V(8); PG8_WAIT_L(0); PG8_BAR; PG8_MMA(0, 0, At, B0); PG8_MMA(0, 1, At, B1); PG8_BAR; PG8_SCHED;
;             PG8_LDA(At, 1, 1); PG8_STAGE(PG8_SB(1, 0), b3, voffB); PG8_STAGE(PG8_SB(1, 1), b3 + hstep, voffB); PG8_STAGE(PG8_SA(1, 0), a3, voffA);
	s_waitcnt lgkmcnt(0)
	v_mfma_f32_16x16x32_bf16 v[60:63], v[128:131], v[174:177], v[60:63]
	v_mfma_f32_16x16x32_bf16 v[56:59], v[136:139], v[174:177], v[56:59]
	v_mfma_f32_16x16x32_bf16 v[44:47], v[128:131], v[188:191], v[44:47]
	v_mfma_f32_16x16x32_bf16 v[40:43], v[136:139], v[188:191], v[40:43]
	v_mfma_f32_16x16x32_bf16 v[28:31], v[128:131], v[196:199], v[28:31]
	v_mfma_f32_16x16x32_bf16 v[24:27], v[136:139], v[196:199], v[24:27]
	v_mfma_f32_16x16x32_bf16 v[12:15], v[128:131], v[220:223], v[12:15]
	v_mfma_f32_16x16x32_bf16 v[8:11], v[136:139], v[220:223], v[8:11]
	v_mfma_f32_16x16x32_bf16 v[60:63], v[132:135], v[184:187], v[60:63]
	v_mfma_f32_16x16x32_bf16 v[56:59], v[140:143], v[184:187], v[56:59]
	v_mfma_f32_16x16x32_bf16 v[44:47], v[132:135], v[192:195], v[44:47]
	v_mfma_f32_16x16x32_bf16 v[40:43], v[140:143], v[192:195], v[40:43]
	v_mfma_f32_16x16x32_bf16 v[28:31], v[132:135], v[216:219], v[28:31]
	v_mfma_f32_16x16x32_bf16 v[24:27], v[140:143], v[216:219], v[24:27]
	v_mfma_f32_16x16x32_bf16 v[12:15], v[132:135], v[224:227], v[12:15]
	v_mfma_f32_16x16x32_bf16 v[8:11], v[140:143], v[224:227], v[8:11]
	v_mfma_f32_16x16x32_bf16 v[52:55], v[144:147], v[174:177], v[52:55]
	v_mfma_f32_16x16x32_bf16 v[48:51], v[152:155], v[174:177], v[48:51]
	v_mfma_f32_16x16x32_bf16 v[36:39], v[144:147], v[188:191], v[36:39]
	v_mfma_f32_16x16x32_bf16 v[32:35], v[152:155], v[188:191], v[32:35]
	v_mfma_f32_16x16x32_bf16 v[20:23], v[144:147], v[196:199], v[20:23]
	v_mfma_f32_16x16x32_bf16 v[16:19], v[152:155], v[196:199], v[16:19]
	v_mfma_f32_16x16x32_bf16 v[4:7], v[144:147], v[220:223], v[4:7]
	v_mfma_f32_16x16x32_bf16 v[0:3], v[152:155], v[220:223], v[0:3]
	v_mfma_f32_16x16x32_bf16 v[52:55], v[148:151], v[184:187], v[52:55]
	v_mfma_f32_16x16x32_bf16 v[48:51], v[156:159], v[184:187], v[48:51]
	v_mfma_f32_16x16x32_bf16 v[36:39], v[148:151], v[192:195], v[36:39]
	v_mfma_f32_16x16x32_bf16 v[32:35], v[156:159], v[192:195], v[32:35]
	v_mfma_f32_16x16x32_bf16 v[20:23], v[148:151], v[216:219], v[20:23]
	v_mfma_f32_16x16x32_bf16 v[16:19], v[156:159], v[216:219], v[16:19]
	v_mfma_f32_16x16x32_bf16 v[4:7], v[148:151], v[224:227], v[4:7]
	v_mfma_f32_16x16x32_bf16 v[0:3], v[156:159], v[224:227], v[0:3]
	s_barrier
	s_add_i32 s16, 0, 0x18000
	s_add_i32 s34, 0, 0x1c000
	v_add_u32_e32 v140, s16, v210
	v_add_u32_e32 v156, s34, v210
	ds_read_b128 v[128:131], v140
	ds_read_b128 v[132:135], v140 offset:1024
	ds_read_b128 v[136:139], v140 offset:2048
	ds_read_b128 v[140:143], v140 offset:3072
	ds_read_b128 v[144:147], v156
	ds_read_b128 v[148:151], v156 offset:1024
	ds_read_b128 v[152:155], v156 offset:2048
	ds_read_b128 v[156:159], v156 offset:3072
	s_add_u32 s42, s42, s48
	s_addc_u32 s43, s43, 0
	s_mov_b32 m0, s64
	v_lshl_add_u64 v[236:237], s[42:43], 0, v[164:165]
	ds_read_b128 v[174:177], v215 offset:32768
	ds_read_b128 v[184:187], v215 offset:33792
	ds_read_b128 v[188:191], v215 offset:34816
	ds_read_b128 v[192:195], v215 offset:35840
	ds_read_b128 v[196:199], v215 offset:36864
	ds_read_b128 v[216:219], v215 offset:37888
	ds_read_b128 v[220:223], v215 offset:38912
	ds_read_b128 v[224:227], v215 offset:39936
	global_load_lds_dwordx4 v[236:237], off
	v_lshl_add_u64 v[236:237], s[42:43], 0, v[162:163]
	s_mov_b32 m0, s65
	s_nop 0
	global_load_lds_dwordx4 v[236:237], off
	s_waitcnt vmcnt(8)
	s_waitcnt lgkmcnt(0)
	s_barrier
	s_waitcnt lgkmcnt(0)
	v_mfma_f32_16x16x32_bf16 v[124:127], v[128:131], v[174:177], v[124:127]
	v_mfma_f32_16x16x32_bf16 v[120:123], v[136:139], v[174:177], v[120:123]
	v_mfma_f32_16x16x32_bf16 v[108:111], v[128:131], v[188:191], v[108:111]
	v_mfma_f32_16x16x32_bf16 v[104:107], v[136:139], v[188:191], v[104:107]
	v_mfma_f32_16x16x32_bf16 v[92:95], v[128:131], v[196:199], v[92:95]
	v_mfma_f32_16x16x32_bf16 v[88:91], v[136:139], v[196:199], v[88:91]
	v_mfma_f32_16x16x32_bf16 v[76:79], v[128:131], v[220:223], v[76:79]
	v_mfma_f32_16x16x32_bf16 v[72:75], v[136:139], v[220:223], v[72:75]
	v_mfma_f32_16x16x32_bf16 v[124:127], v[132:135], v[184:187], v[124:127]
	v_mfma_f32_16x16x32_bf16 v[120:123], v[140:143], v[184:187], v[120:123]
	v_mfma_f32_16x16x32_bf16 v[108:111], v[132:135], v[192:195], v[108:111]
	v_mfma_f32_16x16x32_bf16 v[104:107], v[140:143], v[192:195], v[104:107]
	v_mfma_f32_16x16x32_bf16 v[92:95], v[132:135], v[216:219], v[92:95]
	v_mfma_f32_16x16x32_bf16 v[88:91], v[140:143], v[216:219], v[88:91]
	v_mfma_f32_16x16x32_bf16 v[76:79], v[132:135], v[224:227], v[76:79]
	v_mfma_f32_16x16x32_bf16 v[72:75], v[140:143], v[224:227], v[72:75]
	v_mfma_f32_16x16x32_bf16 v[116:119], v[144:147], v[174:177], v[116:119]
	v_mfma_f32_16x16x32_bf16 v[112:115], v[152:155], v[174:177], v[112:115]
	v_mfma_f32_16x16x32_bf16 v[100:103], v[144:147], v[188:191], v[100:103]
	v_mfma_f32_16x16x32_bf16 v[96:99], v[152:155], v[188:191], v[96:99]
	v_mfma_f32_16x16x32_bf16 v[84:87], v[144:147], v[196:199], v[84:87]
	v_mfma_f32_16x16x32_bf16 v[80:83], v[152:155], v[196:199], v[80:83]
	v_mfma_f32_16x16x32_bf16 v[68:71], v[144:147], v[220:223], v[68:71]
	v_mfma_f32_16x16x32_bf16 v[64:67], v[152:155], v[220:223], v[64:67]
	v_mfma_f32_16x16x32_bf16 v[116:119], v[148:151], v[184:187], v[116:119]
	v_mfma_f32_16x16x32_bf16 v[112:115], v[156:159], v[184:187], v[112:115]
	v_mfma_f32_16x16x32_bf16 v[100:103], v[148:151], v[192:195], v[100:103]
	v_mfma_f32_16x16x32_bf16 v[96:99], v[156:159], v[192:195], v[96:99]
	v_mfma_f32_16x16x32_bf16 v[84:87], v[148:151], v[216:219], v[84:87]
	v_mfma_f32_16x16x32_bf16 v[80:83], v[156:159], v[216:219], v[80:83]
	v_mfma_f32_16x16x32_bf16 v[68:71], v[148:151], v[224:227], v[68:71]
	v_mfma_f32_16x16x32_bf16 v[64:67], v[156:159], v[224:227], v[64:67]
	s_barrier
; #define PG8_STAGE(bufoff, gbase, voff) do { _Pragma("unroll") for (int _i = 0; _i < 2; ++_i) \
;         __builtin_amdgcn_global_load_lds((const unsigned*)((const char*)(gbase) + (voff)[_i]), (PG8_LAS unsigned*)(lds + (bufoff) + ldsw + _i * 8192), 16, 0, 0); } while (0)
; #define PG8_LDA(dst, b, h) do { _Pragma("unroll") for (int m = 0; m < 4; ++m) _Pragma("unroll") for (int k = 0; k < 2; ++k) dst[m][k] = *(const PG8_LAS bf16x8*)(lds + PG8_SA(b, h) + aoff + m * 2048 + k * 1024); } while (0)
; #define PG8_MMA(ai, bj, At, Bt) do { __builtin_amdgcn_s_setprio(1); _Pragma("unroll") for (int m = 0; m < 4; ++m) _Pragma("unroll") for (int n = 0; n < 2; ++n) _Pragma("unroll") for (int k = 0; k < 2; ++k) \
;         acc[ai][bj][m][n] = __builtin_amdgcn_mfma_f32_16x16x32_bf16(Bt[n][k], At[m][k], acc[ai][bj][m][n], 0, 0, 0); __builtin_amdgcn_s_setprio(0); } while (0)
; #define PG8_WAIT_V(n) asm volatile("s_waitcnt vmcnt(" #n ")" ::: "memory")
; #define PG8_WAIT_L(n) asm volatile("s_waitcnt lgkmcnt(" #n ")" ::: "memory")
; #define PG8_BAR __builtin_amdgcn_s_barrier()
; #define PG8_SCHED __builtin_amdgcn_sched_barrier(0)
; template <class Epi, class Sched, bool ALIGN_EPI = false, bool SP2 = false>
; __device__ __forceinline__ void gemm_phase(PG8_LAS unsigned char* lds, const Gemm g, const Sched& S, const Epi& E) {
;     ...
;             PG8_LDA(At, 1, 1); PG8_STAGE(PG8_SB(1, 0), b3, voffB); PG8_STAGE(PG8_SB(1, 1), b3 + hstep, voffB); PG8_STAGE(PG8_SA(1, 0), a3, voffA);
;             PG8_WAIT_V(8); PG8_WAIT_L(0); PG8_BAR; PG8_MMA(1, 0, At, B0); PG8_MMA(1, 1, At, B1); PG8_BAR; PG8_SCHED;
	s_add_i32 s16, s16, s24
	v_lshl_add_u64 v[178:179], v[178:179], 0, s[58:59]
	s_mov_b32 m0, s16
	ds_read_b128 v[174:177], v215 offset:49152
	ds_read_b128 v[184:187], v215 offset:50176
	ds_read_b128 v[188:191], v215 offset:51200
	ds_read_b128 v[192:195], v215 offset:52224
	ds_read_b128 v[196:199], v215 offset:53248
	ds_read_b128 v[216:219], v215 offset:54272
	ds_read_b128 v[220:223], v215 offset:55296
	ds_read_b128 v[224:227], v215 offset:56320
	global_load_lds_dwordx4 v[178:179], off
	v_lshl_add_u64 v[178:179], v[200:201], 0, s[58:59]
	s_add_i32 m0, s16, 0x2000
	s_add_i32 s16, s34, s24
	global_load_lds_dwordx4 v[178:179], off
	v_lshl_add_u64 v[178:179], v[228:229], 0, s[58:59]
	s_mov_b32 m0, s16
	s_nop 0
	global_load_lds_dwordx4 v[178:179], off
	v_lshl_add_u64 v[178:179], v[230:231], 0, s[58:59]
	s_add_i32 m0, s16, 0x2000
	s_nop 0
	global_load_lds_dwordx4 v[178:179], off
	v_lshl_add_u64 v[178:179], v[232:233], 0, s[58:59]
	s_mov_b32 m0, s60
	s_nop 0
	global_load_lds_dwordx4 v[178:179], off
	v_lshl_add_u64 v[178:179], v[234:235], 0, s[58:59]
	s_mov_b32 m0, s61
	s_nop 0
	global_load_lds_dwordx4 v[178:179], off
	s_waitcnt vmcnt(8)
	s_waitcnt lgkmcnt(0)
	s_barrier
	s_waitcnt lgkmcnt(0)
	v_mfma_f32_16x16x32_bf16 v[60:63], v[128:131], v[174:177], v[60:63]
	v_mfma_f32_16x16x32_bf16 v[56:59], v[136:139], v[174:177], v[56:59]
	v_mfma_f32_16x16x32_bf16 v[44:47], v[128:131], v[188:191], v[44:47]
	v_mfma_f32_16x16x32_bf16 v[40:43], v[136:139], v[188:191], v[40:43]
	v_mfma_f32_16x16x32_bf16 v[28:31], v[128:131], v[196:199], v[28:31]
	v_mfma_f32_16x16x32_bf16 v[24:27], v[136:139], v[196:199], v[24:27]
	v_mfma_f32_16x16x32_bf16 v[12:15], v[128:131], v[220:223], v[12:15]
	v_mfma_f32_16x16x32_bf16 v[8:11], v[136:139], v[220:223], v[8:11]
	v_mfma_f32_16x16x32_bf16 v[60:63], v[132:135], v[184:187], v[60:63]
	v_mfma_f32_16x16x32_bf16 v[56:59], v[140:143], v[184:187], v[56:59]
	v_mfma_f32_16x16x32_bf16 v[44:47], v[132:135], v[192:195], v[44:47]
	v_mfma_f32_16x16x32_bf16 v[40:43], v[140:143], v[192:195], v[40:43]
	v_mfma_f32_16x16x32_bf16 v[28:31], v[132:135], v[216:219], v[28:31]
	v_mfma_f32_16x16x32_bf16 v[24:27], v[140:143], v[216:219], v[24:27]
	v_mfma_f32_16x16x32_bf16 v[12:15], v[132:135], v[224:227], v[12:15]
	v_mfma_f32_16x16x32_bf16 v[8:11], v[140:143], v[224:227], v[8:11]
	v_mfma_f32_16x16x32_bf16 v[52:55], v[144:147], v[174:177], v[52:55]
	v_mfma_f32_16x16x32_bf16 v[48:51], v[152:155], v[174:177], v[48:51]
	v_mfma_f32_16x16x32_bf16 v[36:39], v[144:147], v[188:191], v[36:39]
	v_mfma_f32_16x16x32_bf16 v[32:35], v[152:155], v[188:191], v[32:35]
	v_mfma_f32_16x16x32_bf16 v[20:23], v[144:147], v[196:199], v[20:23]
	v_mfma_f32_16x16x32_bf16 v[16:19], v[152:155], v[196:199], v[16:19]
	v_mfma_f32_16x16x32_bf16 v[4:7], v[144:147], v[220:223], v[4:7]
	v_mfma_f32_16x16x32_bf16 v[0:3], v[152:155], v[220:223], v[0:3]
	v_mfma_f32_16x16x32_bf16 v[52:55], v[148:151], v[184:187], v[52:55]
	v_mfma_f32_16x16x32_bf16 v[48:51], v[156:159], v[184:187], v[48:51]
	v_mfma_f32_16x16x32_bf16 v[36:39], v[148:151], v[192:195], v[36:39]
	v_mfma_f32_16x16x32_bf16 v[32:35], v[156:159], v[192:195], v[32:35]
	v_mfma_f32_16x16x32_bf16 v[20:23], v[148:151], v[216:219], v[20:23]
	v_mfma_f32_16x16x32_bf16 v[16:19], v[156:159], v[216:219], v[16:19]
	v_mfma_f32_16x16x32_bf16 v[4:7], v[148:151], v[224:227], v[4:7]
	v_mfma_f32_16x16x32_bf16 v[0:3], v[156:159], v[224:227], v[0:3]
	s_barrier
	s_add_u32 s6, s6, 0x100
	s_addc_u32 s7, s7, 0
	s_add_u32 s50, s50, 0x100
	s_addc_u32 s79, s79, 0
	s_cmp_ge_u32 s97, s26
	s_mov_b32 s42, s97
	s_cbranch_scc0 .LBB0_890
	s_and_b64 vcc, exec, s[30:31]
	s_cbranch_vccz .LBB0_893
	s_barrier

; #define PG8_STAGE(bufoff, gbase, voff) do { _Pragma("unroll") for (int _i = 0; _i < 2; ++_i) \
;         __builtin_amdgcn_global_load_lds((const unsigned*)((const char*)(gbase) + (voff)[_i]), (PG8_LAS unsigned*)(lds + (bufoff) + ldsw + _i * 8192), 16, 0, 0); } while (0)
; #define PG8_LDA(dst, b, h) do { _Pragma("unroll") for (int m = 0; m < 4; ++m) _Pragma("unroll") for (int k = 0; k < 2; ++k) dst[m][k] = *(const PG8_LAS bf16x8*)(lds + PG8_SA(b, h) + aoff + m * 2048 + k * 1024); } while (0)
; #define PG8_LDB(dst, b, h) do { _Pragma("unroll") for (int n = 0; n < 2; ++n) _Pragma("unroll") for (int k = 0; k < 2; ++k) dst[n][k] = *(const PG8_LAS bf16x8*)(lds + PG8_SB(b, h) + boff + n * 2048 + k * 1024); } while (0)
; #define PG8_MMA(ai, bj, At, Bt) do { __builtin_amdgcn_s_setprio(1); _Pragma("unroll") for (int m = 0; m < 4; ++m) _Pragma("unroll") for (int n = 0; n < 2; ++n) _Pragma("unroll") for (int k = 0; k < 2; ++k) \
;         acc[ai][bj][m][n] = __builtin_amdgcn_mfma_f32_16x16x32_bf16(Bt[n][k], At[m][k], acc[ai][bj][m][n], 0, 0, 0); __builtin_amdgcn_s_setprio(0); } while (0)
; #define PG8_WAIT_V(n) asm volatile("s_waitcnt vmcnt(" #n ")" ::: "memory")
; #define PG8_WAIT_L(n) asm volatile("s_waitcnt lgkmcnt(" #n ")" ::: "memory")
; #define PG8_BAR __builtin_amdgcn_s_barrier()
; #define PG8_SCHED __builtin_amdgcn_sched_barrier(0)
; template <class Epi, class Sched, bool ALIGN_EPI = false, bool SP2 = false>
; __device__ __forceinline__ void gemm_phase(PG8_LAS unsigned char* lds, const Gemm g, const Sched& S, const Epi& E) {
;     ...
;             PG8_LDB(B0, 0, 0); PG8_LDB(B1, 0, 1); PG8_SCHED; PG8_LDA(At, 0, 0); PG8_STAGE(PG8_SA(1, 1), a1 + hstep, voffA);
;             PG8_WAIT_V(8); PG8_WAIT_L(0); PG8_BAR; PG8_MMA(0, 0, At, B0); PG8_MMA(0, 1, At, B1); PG8_BAR; PG8_SCHED;
;             PG8_LDA(At, 0, 1); PG8_STAGE(PG8_SB(0, 0), b2, voffB); PG8_STAGE(PG8_SB(0, 1), b2 + hstep, voffB); PG8_STAGE(PG8_SA(0, 0), a2, voffA);
;             PG8_WAIT_V(8); PG8_WAIT_L(0); PG8_BAR; PG8_MMA(1, 0, At, B0); PG8_MMA(1, 1, At, B1); PG8_BAR; PG8_SCHED;
.LBB0_1067:
	s_add_u32 s16, s6, 0xfffc0080
	s_addc_u32 s34, s7, -1
	s_add_i32 s35, 0, 0x10000
	s_cmp_eq_u32 s47, 12
	s_cselect_b32 s53, s25, s34
	s_cselect_b32 s52, s26, s16
	v_add_u32_e32 v147, s35, v145
	s_cselect_b32 s49, s27, s45
	s_cselect_b32 s48, s29, s31
	s_add_i32 s16, 0, 0x14000
	ds_read_b128 v[140:143], v147
	ds_read_b128 v[148:151], v147 offset:1024
	ds_read_b128 v[152:155], v147 offset:2048
	ds_read_b128 v[156:159], v147 offset:3072
	v_add_u32_e32 v147, s16, v145
	ds_read_b128 v[160:163], v147
	ds_read_b128 v[164:167], v147 offset:1024
	ds_read_b128 v[168:171], v147 offset:2048
	ds_read_b128 v[172:175], v147 offset:3072
	v_lshl_add_u64 v[200:201], s[6:7], 0, v[136:137]
	s_add_i32 m0, s15, 0xc000
	ds_read_b128 v[176:179], v146
	ds_read_b128 v[184:187], v146 offset:1024
	ds_read_b128 v[188:191], v146 offset:2048
	ds_read_b128 v[192:195], v146 offset:3072
	ds_read_b128 v[196:199], v146 offset:4096
	ds_read_b128 v[210:213], v146 offset:5120
	ds_read_b128 v[214:217], v146 offset:6144
	ds_read_b128 v[218:221], v146 offset:7168
	global_load_lds_dwordx4 v[200:201], off
	v_lshl_add_u64 v[200:201], s[6:7], 0, v[138:139]
	s_add_i32 m0, s15, 0xe000
	s_nop 0
	global_load_lds_dwordx4 v[200:201], off
	s_waitcnt vmcnt(8)
	s_waitcnt lgkmcnt(0)
	s_barrier
	s_waitcnt lgkmcnt(0)
	v_mfma_f32_16x16x32_bf16 v[124:127], v[140:143], v[176:179], v[124:127]
	v_mfma_f32_16x16x32_bf16 v[120:123], v[152:155], v[176:179], v[120:123]
	v_mfma_f32_16x16x32_bf16 v[108:111], v[140:143], v[188:191], v[108:111]
	v_mfma_f32_16x16x32_bf16 v[104:107], v[152:155], v[188:191], v[104:107]
	v_mfma_f32_16x16x32_bf16 v[92:95], v[140:143], v[196:199], v[92:95]
	v_mfma_f32_16x16x32_bf16 v[88:91], v[152:155], v[196:199], v[88:91]
	v_mfma_f32_16x16x32_bf16 v[76:79], v[140:143], v[214:217], v[76:79]
	v_mfma_f32_16x16x32_bf16 v[72:75], v[152:155], v[214:217], v[72:75]
	v_mfma_f32_16x16x32_bf16 v[124:127], v[148:151], v[184:187], v[124:127]
	v_mfma_f32_16x16x32_bf16 v[120:123], v[156:159], v[184:187], v[120:123]
	v_mfma_f32_16x16x32_bf16 v[108:111], v[148:151], v[192:195], v[108:111]
	v_mfma_f32_16x16x32_bf16 v[104:107], v[156:159], v[192:195], v[104:107]
	v_mfma_f32_16x16x32_bf16 v[92:95], v[148:151], v[210:213], v[92:95]
	v_mfma_f32_16x16x32_bf16 v[88:91], v[156:159], v[210:213], v[88:91]
	v_mfma_f32_16x16x32_bf16 v[76:79], v[148:151], v[218:221], v[76:79]
	v_mfma_f32_16x16x32_bf16 v[72:75], v[156:159], v[218:221], v[72:75]
	v_mfma_f32_16x16x32_bf16 v[116:119], v[160:163], v[176:179], v[116:119]
	v_mfma_f32_16x16x32_bf16 v[112:115], v[168:171], v[176:179], v[112:115]
	v_mfma_f32_16x16x32_bf16 v[100:103], v[160:163], v[188:191], v[100:103]
	v_mfma_f32_16x16x32_bf16 v[96:99], v[168:171], v[188:191], v[96:99]
	v_mfma_f32_16x16x32_bf16 v[84:87], v[160:163], v[196:199], v[84:87]
	v_mfma_f32_16x16x32_bf16 v[80:83], v[168:171], v[196:199], v[80:83]
	v_mfma_f32_16x16x32_bf16 v[68:71], v[160:163], v[214:217], v[68:71]
	v_mfma_f32_16x16x32_bf16 v[64:67], v[168:171], v[214:217], v[64:67]
	v_mfma_f32_16x16x32_bf16 v[116:119], v[164:167], v[184:187], v[116:119]
	v_mfma_f32_16x16x32_bf16 v[112:115], v[172:175], v[184:187], v[112:115]
	v_mfma_f32_16x16x32_bf16 v[100:103], v[164:167], v[192:195], v[100:103]
	v_mfma_f32_16x16x32_bf16 v[96:99], v[172:175], v[192:195], v[96:99]
	v_mfma_f32_16x16x32_bf16 v[84:87], v[164:167], v[210:213], v[84:87]
	v_mfma_f32_16x16x32_bf16 v[80:83], v[172:175], v[210:213], v[80:83]
	v_mfma_f32_16x16x32_bf16 v[68:71], v[164:167], v[218:221], v[68:71]
	v_mfma_f32_16x16x32_bf16 v[64:67], v[172:175], v[218:221], v[64:67]
	s_barrier
	s_add_i32 s34, s35, s13
	v_lshl_add_u64 v[200:201], s[48:49], 0, v[130:131]
	s_mov_b32 m0, s34
	ds_read_b128 v[176:179], v146 offset:16384
	ds_read_b128 v[184:187], v146 offset:17408
	ds_read_b128 v[188:191], v146 offset:18432
	ds_read_b128 v[192:195], v146 offset:19456
	ds_read_b128 v[196:199], v146 offset:20480
	ds_read_b128 v[210:213], v146 offset:21504
	ds_read_b128 v[214:217], v146 offset:22528
	ds_read_b128 v[218:221], v146 offset:23552
	global_load_lds_dwordx4 v[200:201], off
	s_add_i32 m0, s34, 0x2000
	s_add_u32 s34, s48, 0x40000
	v_lshl_add_u64 v[222:223], s[48:49], 0, v[134:135]
	s_addc_u32 s35, s49, 0
	s_add_i32 s16, s16, s13
	global_load_lds_dwordx4 v[222:223], off
	v_lshl_add_u64 v[224:225], s[34:35], 0, v[130:131]
	s_mov_b32 m0, s16
	v_lshl_add_u64 v[226:227], s[52:53], 0, v[132:133]
	global_load_lds_dwordx4 v[224:225], off
	v_lshl_add_u64 v[224:225], s[34:35], 0, v[134:135]
	s_add_i32 m0, s16, 0x2000
	s_nop 0
	global_load_lds_dwordx4 v[224:225], off
	v_lshl_add_u64 v[224:225], s[52:53], 0, v[128:129]
	s_mov_b32 m0, s15
	s_nop 0
	global_load_lds_dwordx4 v[224:225], off
	s_mov_b32 m0, s19
	s_nop 0
	global_load_lds_dwordx4 v[226:227], off
	s_waitcnt vmcnt(8)
	s_waitcnt lgkmcnt(0)
	s_barrier
; #define PG8_STAGE(bufoff, gbase, voff) do { _Pragma("unroll") for (int _i = 0; _i < 2; ++_i) \
;         __builtin_amdgcn_global_load_lds((const unsigned*)((const char*)(gbase) + (voff)[_i]), (PG8_LAS unsigned*)(lds + (bufoff) + ldsw + _i * 8192), 16, 0, 0); } while (0)
; #define PG8_LDA(dst, b, h) do { _Pragma("unroll") for (int m = 0; m < 4; ++m) _Pragma("unroll") for (int k = 0; k < 2; ++k) dst[m][k] = *(const PG8_LAS bf16x8*)(lds + PG8_SA(b, h) + aoff + m * 2048 + k * 1024); } while (0)
; #define PG8_LDB(dst, b, h) do { _Pragma("unroll") for (int n = 0; n < 2; ++n) _Pragma("unroll") for (int k = 0; k < 2; ++k) dst[n][k] = *(const PG8_LAS bf16x8*)(lds + PG8_SB(b, h) + boff + n * 2048 + k * 1024); } while (0)
; #define PG8_MMA(ai, bj, At, Bt) do { __builtin_amdgcn_s_setprio(1); _Pragma("unroll") for (int m = 0; m < 4; ++m) _Pragma("unroll") for (int n = 0; n < 2; ++n) _Pragma("unroll") for (int k = 0; k < 2; ++k) \
;         acc[ai][bj][m][n] = __builtin_amdgcn_mfma_f32_16x16x32_bf16(Bt[n][k], At[m][k], acc[ai][bj][m][n], 0, 0, 0); __builtin_amdgcn_s_setprio(0); } while (0)
; #define PG8_WAIT_V(n) asm volatile("s_waitcnt vmcnt(" #n ")" ::: "memory")
; #define PG8_WAIT_L(n) asm volatile("s_waitcnt lgkmcnt(" #n ")" ::: "memory")
; #define PG8_BAR __builtin_amdgcn_s_barrier()
; #define PG8_SCHED __builtin_amdgcn_sched_barrier(0)
; template <class Epi, class Sched, bool ALIGN_EPI = false, bool SP2 = false>
; __device__ __forceinline__ void gemm_phase(PG8_LAS unsigned char* lds, const Gemm g, const Sched& S, const Epi& E) {
;     ...
;             PG8_WAIT_V(8); PG8_WAIT_L(0); PG8_BAR; PG8_MMA(1, 0, At, B0); PG8_MMA(1, 1, At, B1); PG8_BAR; PG8_SCHED;
;             PG8_LDB(B0, 1, 0); PG8_LDB(B1, 1, 1); PG8_SCHED; PG8_LDA(At, 1, 0); PG8_STAGE(PG8_SA(0, 1), a2 + hstep, voffA);
;             PG8_WAIT_V(8); PG8_WAIT_L(0); PG8_BAR; PG8_MMA(0, 0, At, B0); PG8_MMA(0, 1, At, B1); PG8_BAR; PG8_SCHED;
;             PG8_LDA(At, 1, 1); PG8_STAGE(PG8_SB(1, 0), b3, voffB); PG8_STAGE(PG8_SB(1, 1), b3 + hstep, voffB); PG8_STAGE(PG8_SA(1, 0), a3, voffA);
	s_waitcnt lgkmcnt(0)
	v_mfma_f32_16x16x32_bf16 v[60:63], v[140:143], v[176:179], v[60:63]
	v_mfma_f32_16x16x32_bf16 v[56:59], v[152:155], v[176:179], v[56:59]
	v_mfma_f32_16x16x32_bf16 v[44:47], v[140:143], v[188:191], v[44:47]
	v_mfma_f32_16x16x32_bf16 v[40:43], v[152:155], v[188:191], v[40:43]
	v_mfma_f32_16x16x32_bf16 v[28:31], v[140:143], v[196:199], v[28:31]
	v_mfma_f32_16x16x32_bf16 v[24:27], v[152:155], v[196:199], v[24:27]
	v_mfma_f32_16x16x32_bf16 v[12:15], v[140:143], v[214:217], v[12:15]
	v_mfma_f32_16x16x32_bf16 v[8:11], v[152:155], v[214:217], v[8:11]
	v_mfma_f32_16x16x32_bf16 v[60:63], v[148:151], v[184:187], v[60:63]
	v_mfma_f32_16x16x32_bf16 v[56:59], v[156:159], v[184:187], v[56:59]
	v_mfma_f32_16x16x32_bf16 v[44:47], v[148:151], v[192:195], v[44:47]
	v_mfma_f32_16x16x32_bf16 v[40:43], v[156:159], v[192:195], v[40:43]
	v_mfma_f32_16x16x32_bf16 v[28:31], v[148:151], v[210:213], v[28:31]
	v_mfma_f32_16x16x32_bf16 v[24:27], v[156:159], v[210:213], v[24:27]
	v_mfma_f32_16x16x32_bf16 v[12:15], v[148:151], v[218:221], v[12:15]
	v_mfma_f32_16x16x32_bf16 v[8:11], v[156:159], v[218:221], v[8:11]
	v_mfma_f32_16x16x32_bf16 v[52:55], v[160:163], v[176:179], v[52:55]
	v_mfma_f32_16x16x32_bf16 v[48:51], v[168:171], v[176:179], v[48:51]
	v_mfma_f32_16x16x32_bf16 v[36:39], v[160:163], v[188:191], v[36:39]
	v_mfma_f32_16x16x32_bf16 v[32:35], v[168:171], v[188:191], v[32:35]
	v_mfma_f32_16x16x32_bf16 v[20:23], v[160:163], v[196:199], v[20:23]
	v_mfma_f32_16x16x32_bf16 v[16:19], v[168:171], v[196:199], v[16:19]
	v_mfma_f32_16x16x32_bf16 v[4:7], v[160:163], v[214:217], v[4:7]
	v_mfma_f32_16x16x32_bf16 v[0:3], v[168:171], v[214:217], v[0:3]
	v_mfma_f32_16x16x32_bf16 v[52:55], v[164:167], v[184:187], v[52:55]
	v_mfma_f32_16x16x32_bf16 v[48:51], v[172:175], v[184:187], v[48:51]
	v_mfma_f32_16x16x32_bf16 v[36:39], v[164:167], v[192:195], v[36:39]
	v_mfma_f32_16x16x32_bf16 v[32:35], v[172:175], v[192:195], v[32:35]
	v_mfma_f32_16x16x32_bf16 v[20:23], v[164:167], v[210:213], v[20:23]
	v_mfma_f32_16x16x32_bf16 v[16:19], v[172:175], v[210:213], v[16:19]
	v_mfma_f32_16x16x32_bf16 v[4:7], v[164:167], v[218:221], v[4:7]
	v_mfma_f32_16x16x32_bf16 v[0:3], v[172:175], v[218:221], v[0:3]
	s_barrier
	s_add_i32 s16, 0, 0x18000
	v_add_u32_e32 v147, s16, v145
	s_add_i32 s60, 0, 0x1c000
	ds_read_b128 v[140:143], v147
	ds_read_b128 v[148:151], v147 offset:1024
	ds_read_b128 v[152:155], v147 offset:2048
	ds_read_b128 v[156:159], v147 offset:3072
	v_add_u32_e32 v147, s60, v145
	ds_read_b128 v[160:163], v147
	ds_read_b128 v[164:167], v147 offset:1024
	ds_read_b128 v[168:171], v147 offset:2048
	ds_read_b128 v[172:175], v147 offset:3072
	s_add_u32 s34, s52, 0x40000
	s_addc_u32 s35, s53, 0
	s_mov_b32 m0, s20
	v_lshl_add_u64 v[228:229], s[34:35], 0, v[128:129]
	ds_read_b128 v[176:179], v146 offset:32768
	ds_read_b128 v[184:187], v146 offset:33792
	ds_read_b128 v[188:191], v146 offset:34816
	ds_read_b128 v[192:195], v146 offset:35840
	ds_read_b128 v[196:199], v146 offset:36864
	ds_read_b128 v[210:213], v146 offset:37888
	ds_read_b128 v[214:217], v146 offset:38912
	ds_read_b128 v[218:221], v146 offset:39936
	global_load_lds_dwordx4 v[228:229], off
	v_lshl_add_u64 v[228:229], s[34:35], 0, v[132:133]
	s_mov_b32 m0, s21
	s_nop 0
	global_load_lds_dwordx4 v[228:229], off
	s_waitcnt vmcnt(8)
	s_waitcnt lgkmcnt(0)
	s_barrier
	s_waitcnt lgkmcnt(0)
	v_mfma_f32_16x16x32_bf16 v[124:127], v[140:143], v[176:179], v[124:127]
	v_mfma_f32_16x16x32_bf16 v[120:123], v[152:155], v[176:179], v[120:123]
	v_mfma_f32_16x16x32_bf16 v[108:111], v[140:143], v[188:191], v[108:111]
	v_mfma_f32_16x16x32_bf16 v[104:107], v[152:155], v[188:191], v[104:107]
	v_mfma_f32_16x16x32_bf16 v[92:95], v[140:143], v[196:199], v[92:95]
	v_mfma_f32_16x16x32_bf16 v[88:91], v[152:155], v[196:199], v[88:91]
	v_mfma_f32_16x16x32_bf16 v[76:79], v[140:143], v[214:217], v[76:79]
	v_mfma_f32_16x16x32_bf16 v[72:75], v[152:155], v[214:217], v[72:75]
	v_mfma_f32_16x16x32_bf16 v[124:127], v[148:151], v[184:187], v[124:127]
	v_mfma_f32_16x16x32_bf16 v[120:123], v[156:159], v[184:187], v[120:123]
	v_mfma_f32_16x16x32_bf16 v[108:111], v[148:151], v[192:195], v[108:111]
	v_mfma_f32_16x16x32_bf16 v[104:107], v[156:159], v[192:195], v[104:107]
	v_mfma_f32_16x16x32_bf16 v[92:95], v[148:151], v[210:213], v[92:95]
	v_mfma_f32_16x16x32_bf16 v[88:91], v[156:159], v[210:213], v[88:91]
	v_mfma_f32_16x16x32_bf16 v[76:79], v[148:151], v[218:221], v[76:79]
	v_mfma_f32_16x16x32_bf16 v[72:75], v[156:159], v[218:221], v[72:75]
	v_mfma_f32_16x16x32_bf16 v[116:119], v[160:163], v[176:179], v[116:119]
	v_mfma_f32_16x16x32_bf16 v[112:115], v[168:171], v[176:179], v[112:115]
	v_mfma_f32_16x16x32_bf16 v[100:103], v[160:163], v[188:191], v[100:103]
	v_mfma_f32_16x16x32_bf16 v[96:99], v[168:171], v[188:191], v[96:99]
	v_mfma_f32_16x16x32_bf16 v[84:87], v[160:163], v[196:199], v[84:87]
	v_mfma_f32_16x16x32_bf16 v[80:83], v[168:171], v[196:199], v[80:83]
	v_mfma_f32_16x16x32_bf16 v[68:71], v[160:163], v[214:217], v[68:71]
	v_mfma_f32_16x16x32_bf16 v[64:67], v[168:171], v[214:217], v[64:67]
	v_mfma_f32_16x16x32_bf16 v[116:119], v[164:167], v[184:187], v[116:119]
	v_mfma_f32_16x16x32_bf16 v[112:115], v[172:175], v[184:187], v[112:115]
	v_mfma_f32_16x16x32_bf16 v[100:103], v[164:167], v[192:195], v[100:103]
	v_mfma_f32_16x16x32_bf16 v[96:99], v[172:175], v[192:195], v[96:99]
	v_mfma_f32_16x16x32_bf16 v[84:87], v[164:167], v[210:213], v[84:87]
	v_mfma_f32_16x16x32_bf16 v[80:83], v[172:175], v[210:213], v[80:83]
	v_mfma_f32_16x16x32_bf16 v[68:71], v[164:167], v[218:221], v[68:71]
	v_mfma_f32_16x16x32_bf16 v[64:67], v[172:175], v[218:221], v[64:67]
	s_barrier
; #define PG8_STAGE(bufoff, gbase, voff) do { _Pragma("unroll") for (int _i = 0; _i < 2; ++_i) \
;         __builtin_amdgcn_global_load_lds((const unsigned*)((const char*)(gbase) + (voff)[_i]), (PG8_LAS unsigned*)(lds + (bufoff) + ldsw + _i * 8192), 16, 0, 0); } while (0)
; #define PG8_LDA(dst, b, h) do { _Pragma("unroll") for (int m = 0; m < 4; ++m) _Pragma("unroll") for (int k = 0; k < 2; ++k) dst[m][k] = *(const PG8_LAS bf16x8*)(lds + PG8_SA(b, h) + aoff + m * 2048 + k * 1024); } while (0)
; #define PG8_MMA(ai, bj, At, Bt) do { __builtin_amdgcn_s_setprio(1); _Pragma("unroll") for (int m = 0; m < 4; ++m) _Pragma("unroll") for (int n = 0; n < 2; ++n) _Pragma("unroll") for (int k = 0; k < 2; ++k) \
;         acc[ai][bj][m][n] = __builtin_amdgcn_mfma_f32_16x16x32_bf16(Bt[n][k], At[m][k], acc[ai][bj][m][n], 0, 0, 0); __builtin_amdgcn_s_setprio(0); } while (0)
; #define PG8_WAIT_V(n) asm volatile("s_waitcnt vmcnt(" #n ")" ::: "memory")
; #define PG8_WAIT_L(n) asm volatile("s_waitcnt lgkmcnt(" #n ")" ::: "memory")
; #define PG8_BAR __builtin_amdgcn_s_barrier()
; #define PG8_SCHED __builtin_amdgcn_sched_barrier(0)
; template <class Epi, class Sched, bool ALIGN_EPI = false, bool SP2 = false>
; __device__ __forceinline__ void gemm_phase(PG8_LAS unsigned char* lds, const Gemm g, const Sched& S, const Epi& E) {
;     ...
;             PG8_LDA(At, 1, 1); PG8_STAGE(PG8_SB(1, 0), b3, voffB); PG8_STAGE(PG8_SB(1, 1), b3 + hstep, voffB); PG8_STAGE(PG8_SA(1, 0), a3, voffA);
;             PG8_WAIT_V(8); PG8_WAIT_L(0); PG8_BAR; PG8_MMA(1, 0, At, B0); PG8_MMA(1, 1, At, B1); PG8_BAR; PG8_SCHED;
	s_add_i32 s16, s16, s13
	v_lshl_add_u64 v[200:201], v[200:201], 0, s[58:59]
	s_mov_b32 m0, s16
	ds_read_b128 v[176:179], v146 offset:49152
	ds_read_b128 v[184:187], v146 offset:50176
	ds_read_b128 v[188:191], v146 offset:51200
	ds_read_b128 v[192:195], v146 offset:52224
	ds_read_b128 v[196:199], v146 offset:53248
	ds_read_b128 v[210:213], v146 offset:54272
	ds_read_b128 v[214:217], v146 offset:55296
	ds_read_b128 v[218:221], v146 offset:56320
	global_load_lds_dwordx4 v[200:201], off
	s_add_i32 m0, s16, 0x2000
	s_add_u32 s34, s48, 0x40080
	v_lshl_add_u64 v[200:201], v[222:223], 0, s[58:59]
	s_addc_u32 s35, s49, 0
	s_add_i32 s16, s60, s13
	global_load_lds_dwordx4 v[200:201], off
	v_lshl_add_u64 v[200:201], s[34:35], 0, v[130:131]
	s_mov_b32 m0, s16
	s_nop 0
	global_load_lds_dwordx4 v[200:201], off
	v_lshl_add_u64 v[200:201], s[34:35], 0, v[134:135]
	s_add_i32 m0, s16, 0x2000
	s_nop 0
	global_load_lds_dwordx4 v[200:201], off
	v_lshl_add_u64 v[200:201], v[224:225], 0, s[58:59]
	s_mov_b32 m0, s22
	s_nop 0
	global_load_lds_dwordx4 v[200:201], off
	v_lshl_add_u64 v[200:201], v[226:227], 0, s[58:59]
	s_mov_b32 m0, s23
	s_nop 0
	global_load_lds_dwordx4 v[200:201], off
	s_waitcnt vmcnt(8)
	s_waitcnt lgkmcnt(0)
	s_barrier
	s_waitcnt lgkmcnt(0)
	v_mfma_f32_16x16x32_bf16 v[60:63], v[140:143], v[176:179], v[60:63]
	v_mfma_f32_16x16x32_bf16 v[56:59], v[152:155], v[176:179], v[56:59]
	v_mfma_f32_16x16x32_bf16 v[44:47], v[140:143], v[188:191], v[44:47]
	v_mfma_f32_16x16x32_bf16 v[40:43], v[152:155], v[188:191], v[40:43]
	v_mfma_f32_16x16x32_bf16 v[28:31], v[140:143], v[196:199], v[28:31]
	v_mfma_f32_16x16x32_bf16 v[24:27], v[152:155], v[196:199], v[24:27]
	v_mfma_f32_16x16x32_bf16 v[12:15], v[140:143], v[214:217], v[12:15]
	v_mfma_f32_16x16x32_bf16 v[8:11], v[152:155], v[214:217], v[8:11]
	v_mfma_f32_16x16x32_bf16 v[60:63], v[148:151], v[184:187], v[60:63]
	v_mfma_f32_16x16x32_bf16 v[56:59], v[156:159], v[184:187], v[56:59]
	v_mfma_f32_16x16x32_bf16 v[44:47], v[148:151], v[192:195], v[44:47]
	v_mfma_f32_16x16x32_bf16 v[40:43], v[156:159], v[192:195], v[40:43]
	v_mfma_f32_16x16x32_bf16 v[28:31], v[148:151], v[210:213], v[28:31]
	v_mfma_f32_16x16x32_bf16 v[24:27], v[156:159], v[210:213], v[24:27]
	v_mfma_f32_16x16x32_bf16 v[12:15], v[148:151], v[218:221], v[12:15]
	v_mfma_f32_16x16x32_bf16 v[8:11], v[156:159], v[218:221], v[8:11]
	v_mfma_f32_16x16x32_bf16 v[52:55], v[160:163], v[176:179], v[52:55]
	v_mfma_f32_16x16x32_bf16 v[48:51], v[168:171], v[176:179], v[48:51]
	v_mfma_f32_16x16x32_bf16 v[36:39], v[160:163], v[188:191], v[36:39]
	v_mfma_f32_16x16x32_bf16 v[32:35], v[168:171], v[188:191], v[32:35]
	v_mfma_f32_16x16x32_bf16 v[20:23], v[160:163], v[196:199], v[20:23]
	v_mfma_f32_16x16x32_bf16 v[16:19], v[168:171], v[196:199], v[16:19]
	v_mfma_f32_16x16x32_bf16 v[4:7], v[160:163], v[214:217], v[4:7]
	v_mfma_f32_16x16x32_bf16 v[0:3], v[168:171], v[214:217], v[0:3]
	v_mfma_f32_16x16x32_bf16 v[52:55], v[164:167], v[184:187], v[52:55]
	v_mfma_f32_16x16x32_bf16 v[48:51], v[172:175], v[184:187], v[48:51]
	v_mfma_f32_16x16x32_bf16 v[36:39], v[164:167], v[192:195], v[36:39]
	v_mfma_f32_16x16x32_bf16 v[32:35], v[172:175], v[192:195], v[32:35]
	v_mfma_f32_16x16x32_bf16 v[20:23], v[164:167], v[210:213], v[20:23]
	v_mfma_f32_16x16x32_bf16 v[16:19], v[172:175], v[210:213], v[16:19]
	v_mfma_f32_16x16x32_bf16 v[4:7], v[164:167], v[218:221], v[4:7]
	v_mfma_f32_16x16x32_bf16 v[0:3], v[172:175], v[218:221], v[0:3]
	s_barrier
	s_add_i32 s47, s47, 2
	s_add_u32 s6, s6, 0x100
	s_addc_u32 s7, s7, 0
	s_add_u32 s31, s31, 0x100
	s_addc_u32 s45, s45, 0
	s_cmp_gt_u32 s47, 13
	s_cbranch_scc0 .LBB0_1067
	s_and_b64 vcc, exec, s[4:5]
	s_cbranch_vccz .LBB0_1070
	s_barrier
